# EpiResid epilogues (phases F and I) also rewritten: residual x loads batched and pipelined with counted vmcnt instead of per-chunk load+vmcnt(0)
# speedup vs baseline: 1.0083x; 1.0083x over previous
; __device__ __forceinline__ float bflo(unsigned w) { return __uint_as_float(w << 16); }
; __device__ __forceinline__ float bfhi(unsigned w) { return __uint_as_float(w & 0xffff0000u); }
; __device__ __forceinline__ u32x4 pack8u(f32x4 a, f32x4 b) { u32x4 w = {cvt_pk_bf16(a[0], a[1]), cvt_pk_bf16(a[2], a[3]), cvt_pk_bf16(b[0], b[1]), cvt_pk_bf16(b[2], b[3])}; return w; }
; template <class Epi>
; __device__ __forceinline__ void gemm_phase(LAS unsigned char* lds, const Gemm g, const Epi& E) {
;     ...
;         E(acc, cur, wr, wc, fr, fq);
;         if (!has_next) break;
; #pragma unroll
;         for (int a = 0; a < 2; ++a)
; #pragma unroll
;             for (int b = 0; b < 2; ++b)
; #pragma unroll
;                 for (int m = 0; m < 4; ++m)
; #pragma unroll
;                     for (int n = 0; n < 2; ++n) acc[a][b][m][n] = (f32x4){0.f, 0.f, 0.f, 0.f};
;         cur = nxt; cA = nA; cB = nB; ++ui;
;     }
;     __device__ __forceinline__ void operator()(const AccT& acc, const Unit& u, int wr, int wc, int fr, int fq) const {
;     ...
;                     if (XINF) { x0 = *(const f32x4*)(XINF + off); x1 = *(const f32x4*)(XINF + off + 4); }
;                     else { const u32x4 w = *(const u32x4*)(XIN16 + off); x0 = (f32x4){bflo(w[0]), bfhi(w[0]), bflo(w[1]), bfhi(w[1])}; x1 = (f32x4){bflo(w[2]), bfhi(w[2]), bflo(w[3]), bfhi(w[3])}; }
;                     *(u32x4*)(XOUT + off) = pack8u(x0 + gt[bj][0] * acc[ai][bj][m][0], x1 + gt[bj][1] * acc[ai][bj][m][1]);
.Lepr1_latch:
	s_and_b64 vcc, exec, s[40:41]
	s_mov_b32 s96, s48
	s_mov_b32 s42, s64
	s_mov_b64 s[28:29], s[94:95]
	s_mov_b64 s[26:27], s[88:89]
	v_readlane_b32 s94, v255, 26
	v_readlane_b32 s88, v255, 27
	s_mov_b32 s89, 0xc000
	s_movk_i32 s95, 0x1ff
	s_cbranch_vccnz .LBB0_185

; #define PG8_STAGE(bufoff, gbase, voff) do { _Pragma("unroll") for (int _i = 0; _i < 2; ++_i) \
;         __builtin_amdgcn_global_load_lds((const unsigned*)((const char*)(gbase) + (voff)[_i]), (LAS unsigned*)(lds + (bufoff) + ldsw + _i * 8192), 16, 0, 0); } while (0)
; #define PG8_LDA(dst, b, h) do { _Pragma("unroll") for (int m = 0; m < 4; ++m) _Pragma("unroll") for (int k = 0; k < 2; ++k) dst[m][k] = *(const LAS bf16x8*)(lds + PG8_SA(b, h) + aoff + m * 2048 + k * 1024); } while (0)
; #define PG8_LDB(dst, b, h) do { _Pragma("unroll") for (int n = 0; n < 2; ++n) _Pragma("unroll") for (int k = 0; k < 2; ++k) dst[n][k] = *(const LAS bf16x8*)(lds + PG8_SB(b, h) + boff + n * 2048 + k * 1024); } while (0)
; #define PG8_MMA(ai, bj, At, Bt) do { __builtin_amdgcn_s_setprio(1); _Pragma("unroll") for (int m = 0; m < 4; ++m) _Pragma("unroll") for (int n = 0; n < 2; ++n) _Pragma("unroll") for (int k = 0; k < 2; ++k) \
;         acc[ai][bj][m][n] = __builtin_amdgcn_mfma_f32_16x16x32_bf16(Bt[n][k], At[m][k], acc[ai][bj][m][n], 0, 0, 0); __builtin_amdgcn_s_setprio(0); } while (0)
; #define PG8_WAIT_L(n) asm volatile("s_waitcnt lgkmcnt(" #n ")" ::: "memory")
; #define PG8_BAR __builtin_amdgcn_s_barrier()
; #define PG8_SCHED __builtin_amdgcn_sched_barrier(0)
; template <class Epi>
; __device__ __forceinline__ void gemm_phase(LAS unsigned char* lds, const Gemm g, const Epi& E) {
;     ...
;             PG8_LDB(B0, 0, 0); PG8_SCHED; PG8_LDA(At, 0, 0); PG8_STAGE(PG8_SA(1, 1), a1 + hstep, voffA);
;             PG8_WAIT_L(8); PG8_BAR; PG8_WAIT_L(0); PG8_MMA(0, 0, At, B0); PG8_BAR; PG8_SCHED;
;             PG8_LDB(B1, 0, 1); PG8_STAGE(PG8_SB(0, 0), b2, voffB);
;             PG8_BAR; PG8_WAIT_L(0); PG8_MMA(0, 1, At, B1); PG8_BAR;
;             PG8_LDA(At, 0, 1); PG8_STAGE(PG8_SA(0, 0), a2, voffA);
;             PG8_BAR; PG8_WAIT_L(0); PG8_MMA(1, 0, At, B0); PG8_BAR; PG8_SCHED;
.LBB0_120:
	s_add_u32 s28, s26, 0xfff80080
	s_addc_u32 s29, s27, -1
	s_add_i32 s34, 0, 0x10000
	v_add_u32_e32 v92, s34, v174
	ds_read_b128 v[72:75], v92
	ds_read_b128 v[76:79], v92 offset:1024
	ds_read_b128 v[84:87], v92 offset:2048
	ds_read_b128 v[92:95], v92 offset:3072
	s_cmp_eq_u32 vcc_lo, 28
	s_cselect_b32 s37, s38, s29
	s_cselect_b32 s36, s39, s28
	s_cselect_b32 s29, s43, s97
	s_cselect_b32 s28, s49, s65
	v_lshl_add_u64 v[172:173], s[26:27], 0, v[160:161]
	s_add_i32 m0, s68, 0xc000
	ds_read_b128 v[144:147], v175
	ds_read_b128 v[148:151], v175 offset:1024
	ds_read_b128 v[164:167], v175 offset:2048
	ds_read_b128 v[168:171], v175 offset:3072
	ds_read_b128 v[178:181], v175 offset:4096
	ds_read_b128 v[182:185], v175 offset:5120
	ds_read_b128 v[186:189], v175 offset:6144
	ds_read_b128 v[190:193], v175 offset:7168
	global_load_lds_dwordx4 v[172:173], off
	v_lshl_add_u64 v[172:173], s[26:27], 0, v[162:163]
	s_add_i32 m0, s68, 0xe000
	s_nop 0
	global_load_lds_dwordx4 v[172:173], off
	s_waitcnt lgkmcnt(8)
	s_barrier
	s_waitcnt lgkmcnt(0)
	s_setprio 1
	s_waitcnt lgkmcnt(0)
	v_mfma_f32_16x16x32_bf16 v[140:143], v[72:75], v[144:147], v[140:143]
	v_mfma_f32_16x16x32_bf16 v[136:139], v[84:87], v[144:147], v[136:139]
	v_mfma_f32_16x16x32_bf16 v[124:127], v[72:75], v[164:167], v[124:127]
	v_mfma_f32_16x16x32_bf16 v[120:123], v[84:87], v[164:167], v[120:123]
	v_mfma_f32_16x16x32_bf16 v[108:111], v[72:75], v[178:181], v[108:111]
	v_mfma_f32_16x16x32_bf16 v[104:107], v[84:87], v[178:181], v[104:107]
	v_mfma_f32_16x16x32_bf16 v[88:91], v[72:75], v[186:189], v[88:91]
	v_mfma_f32_16x16x32_bf16 v[80:83], v[84:87], v[186:189], v[80:83]
	v_mfma_f32_16x16x32_bf16 v[140:143], v[76:79], v[148:151], v[140:143]
	v_mfma_f32_16x16x32_bf16 v[136:139], v[92:95], v[148:151], v[136:139]
	v_mfma_f32_16x16x32_bf16 v[124:127], v[76:79], v[168:171], v[124:127]
	v_mfma_f32_16x16x32_bf16 v[120:123], v[92:95], v[168:171], v[120:123]
	v_mfma_f32_16x16x32_bf16 v[108:111], v[76:79], v[182:185], v[108:111]
	v_mfma_f32_16x16x32_bf16 v[104:107], v[92:95], v[182:185], v[104:107]
	v_mfma_f32_16x16x32_bf16 v[88:91], v[76:79], v[190:193], v[88:91]
	v_mfma_f32_16x16x32_bf16 v[80:83], v[92:95], v[190:193], v[80:83]
	s_setprio 0
	s_barrier
	s_add_i32 s46, 0, 0x14000
	v_add_u32_e32 v172, s46, v174
	s_add_i32 s34, s34, s31
	ds_read_b128 v[194:197], v172
	ds_read_b128 v[198:201], v172 offset:1024
	ds_read_b128 v[202:205], v172 offset:2048
	ds_read_b128 v[228:231], v172 offset:3072
	v_lshl_add_u64 v[172:173], s[28:29], 0, v[208:209]
	s_mov_b32 m0, s34
	v_lshl_add_u64 v[206:207], s[28:29], 0, v[156:157]
	global_load_lds_dwordx4 v[172:173], off
	s_add_i32 m0, s34, 0x2000
	s_nop 0
	global_load_lds_dwordx4 v[206:207], off
	s_barrier
	s_waitcnt lgkmcnt(0)
	s_setprio 1
	s_waitcnt lgkmcnt(0)
	v_mfma_f32_16x16x32_bf16 v[132:135], v[194:197], v[144:147], v[132:135]
	v_mfma_f32_16x16x32_bf16 v[128:131], v[202:205], v[144:147], v[128:131]
	v_mfma_f32_16x16x32_bf16 v[116:119], v[194:197], v[164:167], v[116:119]
	v_mfma_f32_16x16x32_bf16 v[112:115], v[202:205], v[164:167], v[112:115]
	v_mfma_f32_16x16x32_bf16 v[100:103], v[194:197], v[178:181], v[100:103]
	v_mfma_f32_16x16x32_bf16 v[96:99], v[202:205], v[178:181], v[96:99]
	v_mfma_f32_16x16x32_bf16 v[68:71], v[194:197], v[186:189], v[68:71]
	v_mfma_f32_16x16x32_bf16 v[64:67], v[202:205], v[186:189], v[64:67]
	v_mfma_f32_16x16x32_bf16 v[132:135], v[198:201], v[148:151], v[132:135]
	v_mfma_f32_16x16x32_bf16 v[128:131], v[228:231], v[148:151], v[128:131]
	v_mfma_f32_16x16x32_bf16 v[116:119], v[198:201], v[168:171], v[116:119]
	v_mfma_f32_16x16x32_bf16 v[112:115], v[228:231], v[168:171], v[112:115]
	v_mfma_f32_16x16x32_bf16 v[100:103], v[198:201], v[182:185], v[100:103]
	v_mfma_f32_16x16x32_bf16 v[96:99], v[228:231], v[182:185], v[96:99]
	v_mfma_f32_16x16x32_bf16 v[68:71], v[198:201], v[190:193], v[68:71]
	v_mfma_f32_16x16x32_bf16 v[64:67], v[228:231], v[190:193], v[64:67]
	s_setprio 0
	s_mov_b32 m0, s68
	v_lshl_add_u64 v[220:221], s[36:37], 0, v[152:153]
	s_barrier
	ds_read_b128 v[144:147], v175 offset:16384
	ds_read_b128 v[148:151], v175 offset:17408
	ds_read_b128 v[164:167], v175 offset:18432
	ds_read_b128 v[168:171], v175 offset:19456
	ds_read_b128 v[178:181], v175 offset:20480
	ds_read_b128 v[182:185], v175 offset:21504
	ds_read_b128 v[186:189], v175 offset:22528
	ds_read_b128 v[190:193], v175 offset:23552
	global_load_lds_dwordx4 v[220:221], off
	v_lshl_add_u64 v[232:233], s[36:37], 0, v[154:155]
	s_mov_b32 m0, s69
	s_nop 0
	global_load_lds_dwordx4 v[232:233], off
	s_barrier
	s_waitcnt lgkmcnt(0)
	s_setprio 1
	s_waitcnt lgkmcnt(0)
	v_mfma_f32_16x16x32_bf16 v[60:63], v[72:75], v[144:147], v[60:63]
	v_mfma_f32_16x16x32_bf16 v[56:59], v[84:87], v[144:147], v[56:59]
	v_mfma_f32_16x16x32_bf16 v[44:47], v[72:75], v[164:167], v[44:47]
	v_mfma_f32_16x16x32_bf16 v[40:43], v[84:87], v[164:167], v[40:43]
	v_mfma_f32_16x16x32_bf16 v[28:31], v[72:75], v[178:181], v[28:31]
	v_mfma_f32_16x16x32_bf16 v[24:27], v[84:87], v[178:181], v[24:27]
	v_mfma_f32_16x16x32_bf16 v[12:15], v[72:75], v[186:189], v[12:15]
	v_mfma_f32_16x16x32_bf16 v[8:11], v[84:87], v[186:189], v[8:11]
	v_mfma_f32_16x16x32_bf16 v[60:63], v[76:79], v[148:151], v[60:63]
	v_mfma_f32_16x16x32_bf16 v[56:59], v[92:95], v[148:151], v[56:59]
	v_mfma_f32_16x16x32_bf16 v[44:47], v[76:79], v[168:171], v[44:47]
	v_mfma_f32_16x16x32_bf16 v[40:43], v[92:95], v[168:171], v[40:43]
	v_mfma_f32_16x16x32_bf16 v[28:31], v[76:79], v[182:185], v[28:31]
	v_mfma_f32_16x16x32_bf16 v[24:27], v[92:95], v[182:185], v[24:27]
	v_mfma_f32_16x16x32_bf16 v[12:15], v[76:79], v[190:193], v[12:15]
	v_mfma_f32_16x16x32_bf16 v[8:11], v[92:95], v[190:193], v[8:11]
	s_setprio 0
	s_barrier
; #define PG8_STAGE(bufoff, gbase, voff) do { _Pragma("unroll") for (int _i = 0; _i < 2; ++_i) \
;         __builtin_amdgcn_global_load_lds((const unsigned*)((const char*)(gbase) + (voff)[_i]), (LAS unsigned*)(lds + (bufoff) + ldsw + _i * 8192), 16, 0, 0); } while (0)
; #define PG8_LDA(dst, b, h) do { _Pragma("unroll") for (int m = 0; m < 4; ++m) _Pragma("unroll") for (int k = 0; k < 2; ++k) dst[m][k] = *(const LAS bf16x8*)(lds + PG8_SA(b, h) + aoff + m * 2048 + k * 1024); } while (0)
; #define PG8_LDB(dst, b, h) do { _Pragma("unroll") for (int n = 0; n < 2; ++n) _Pragma("unroll") for (int k = 0; k < 2; ++k) dst[n][k] = *(const LAS bf16x8*)(lds + PG8_SB(b, h) + boff + n * 2048 + k * 1024); } while (0)
; #define PG8_MMA(ai, bj, At, Bt) do { __builtin_amdgcn_s_setprio(1); _Pragma("unroll") for (int m = 0; m < 4; ++m) _Pragma("unroll") for (int n = 0; n < 2; ++n) _Pragma("unroll") for (int k = 0; k < 2; ++k) \
;         acc[ai][bj][m][n] = __builtin_amdgcn_mfma_f32_16x16x32_bf16(Bt[n][k], At[m][k], acc[ai][bj][m][n], 0, 0, 0); __builtin_amdgcn_s_setprio(0); } while (0)
; #define PG8_WAIT_V(n) asm volatile("s_waitcnt vmcnt(" #n ")" ::: "memory")
; #define PG8_WAIT_L(n) asm volatile("s_waitcnt lgkmcnt(" #n ")" ::: "memory")
; #define PG8_BAR __builtin_amdgcn_s_barrier()
; #define PG8_SCHED __builtin_amdgcn_sched_barrier(0)
; template <class Epi>
; __device__ __forceinline__ void gemm_phase(LAS unsigned char* lds, const Gemm g, const Epi& E) {
;     ...
;             PG8_STAGE(PG8_SB(0, 1), b2 + hstep, voffB);
;             PG8_WAIT_V(6); PG8_BAR; PG8_MMA(1, 1, At, B1); PG8_BAR;
;             PG8_LDB(B0, 1, 0); PG8_SCHED; PG8_LDA(At, 1, 0); PG8_STAGE(PG8_SA(0, 1), a2 + hstep, voffA);
;             PG8_WAIT_L(8); PG8_BAR; PG8_WAIT_L(0); PG8_MMA(0, 0, At, B0); PG8_BAR; PG8_SCHED;
;             PG8_LDB(B1, 1, 1); PG8_STAGE(PG8_SB(1, 0), b3, voffB);
;             PG8_BAR; PG8_WAIT_L(0); PG8_MMA(0, 1, At, B1); PG8_BAR;
;             PG8_LDA(At, 1, 1); PG8_STAGE(PG8_SA(1, 0), a3, voffA);
;             PG8_BAR; PG8_WAIT_L(0); PG8_MMA(1, 0, At, B0); PG8_BAR; PG8_SCHED;
	s_add_u32 s34, s28, 0x80000
	s_addc_u32 s35, s29, 0
	s_add_i32 s46, s46, s31
	v_lshl_add_u64 v[72:73], s[34:35], 0, v[208:209]
	s_mov_b32 m0, s46
	s_nop 0
	global_load_lds_dwordx4 v[72:73], off
	v_lshl_add_u64 v[72:73], s[34:35], 0, v[156:157]
	s_add_i32 m0, s46, 0x2000
	s_nop 0
	global_load_lds_dwordx4 v[72:73], off
	s_waitcnt vmcnt(6)
	s_barrier
	s_setprio 1
	v_mfma_f32_16x16x32_bf16 v[52:55], v[194:197], v[144:147], v[52:55]
	v_mfma_f32_16x16x32_bf16 v[48:51], v[202:205], v[144:147], v[48:51]
	v_mfma_f32_16x16x32_bf16 v[36:39], v[194:197], v[164:167], v[36:39]
	v_mfma_f32_16x16x32_bf16 v[32:35], v[202:205], v[164:167], v[32:35]
	v_mfma_f32_16x16x32_bf16 v[20:23], v[194:197], v[178:181], v[20:23]
	v_mfma_f32_16x16x32_bf16 v[16:19], v[202:205], v[178:181], v[16:19]
	v_mfma_f32_16x16x32_bf16 v[4:7], v[194:197], v[186:189], v[4:7]
	v_mfma_f32_16x16x32_bf16 v[0:3], v[202:205], v[186:189], v[0:3]
	v_mfma_f32_16x16x32_bf16 v[52:55], v[198:201], v[148:151], v[52:55]
	v_mfma_f32_16x16x32_bf16 v[48:51], v[228:231], v[148:151], v[48:51]
	v_mfma_f32_16x16x32_bf16 v[36:39], v[198:201], v[168:171], v[36:39]
	v_mfma_f32_16x16x32_bf16 v[32:35], v[228:231], v[168:171], v[32:35]
	v_mfma_f32_16x16x32_bf16 v[20:23], v[198:201], v[182:185], v[20:23]
	v_mfma_f32_16x16x32_bf16 v[16:19], v[228:231], v[182:185], v[16:19]
	v_mfma_f32_16x16x32_bf16 v[4:7], v[198:201], v[190:193], v[4:7]
	v_mfma_f32_16x16x32_bf16 v[0:3], v[228:231], v[190:193], v[0:3]
	s_setprio 0
	s_add_i32 s46, 0, 0x18000
	v_add_u32_e32 v92, s46, v174
	s_barrier
	ds_read_b128 v[72:75], v92
	ds_read_b128 v[76:79], v92 offset:1024
	ds_read_b128 v[84:87], v92 offset:2048
	ds_read_b128 v[92:95], v92 offset:3072
	s_add_u32 s34, s36, 0x80000
	s_addc_u32 s35, s37, 0
	s_mov_b32 m0, s70
	v_lshl_add_u64 v[194:195], s[34:35], 0, v[152:153]
	ds_read_b128 v[144:147], v175 offset:32768
	ds_read_b128 v[148:151], v175 offset:33792
	ds_read_b128 v[164:167], v175 offset:34816
	ds_read_b128 v[168:171], v175 offset:35840
	ds_read_b128 v[178:181], v175 offset:36864
	ds_read_b128 v[182:185], v175 offset:37888
	ds_read_b128 v[186:189], v175 offset:38912
	ds_read_b128 v[190:193], v175 offset:39936
	global_load_lds_dwordx4 v[194:195], off
	v_lshl_add_u64 v[194:195], s[34:35], 0, v[154:155]
	s_mov_b32 m0, s71
	s_nop 0
	global_load_lds_dwordx4 v[194:195], off
	s_waitcnt lgkmcnt(8)
	s_barrier
	s_waitcnt lgkmcnt(0)
	s_setprio 1
	s_waitcnt lgkmcnt(0)
	v_mfma_f32_16x16x32_bf16 v[140:143], v[72:75], v[144:147], v[140:143]
	v_mfma_f32_16x16x32_bf16 v[136:139], v[84:87], v[144:147], v[136:139]
	v_mfma_f32_16x16x32_bf16 v[124:127], v[72:75], v[164:167], v[124:127]
	v_mfma_f32_16x16x32_bf16 v[120:123], v[84:87], v[164:167], v[120:123]
	v_mfma_f32_16x16x32_bf16 v[108:111], v[72:75], v[178:181], v[108:111]
	v_mfma_f32_16x16x32_bf16 v[104:107], v[84:87], v[178:181], v[104:107]
	v_mfma_f32_16x16x32_bf16 v[88:91], v[72:75], v[186:189], v[88:91]
	v_mfma_f32_16x16x32_bf16 v[80:83], v[84:87], v[186:189], v[80:83]
	v_mfma_f32_16x16x32_bf16 v[140:143], v[76:79], v[148:151], v[140:143]
	v_mfma_f32_16x16x32_bf16 v[136:139], v[92:95], v[148:151], v[136:139]
	v_mfma_f32_16x16x32_bf16 v[124:127], v[76:79], v[168:171], v[124:127]
	v_mfma_f32_16x16x32_bf16 v[120:123], v[92:95], v[168:171], v[120:123]
	v_mfma_f32_16x16x32_bf16 v[108:111], v[76:79], v[182:185], v[108:111]
	v_mfma_f32_16x16x32_bf16 v[104:107], v[92:95], v[182:185], v[104:107]
	v_mfma_f32_16x16x32_bf16 v[88:91], v[76:79], v[190:193], v[88:91]
	v_mfma_f32_16x16x32_bf16 v[80:83], v[92:95], v[190:193], v[80:83]
	s_setprio 0
	s_barrier
	s_add_i32 s34, 0, 0x1c000
	s_add_i32 s35, s46, s31
	v_add_u32_e32 v177, s34, v174
	v_lshl_add_u64 v[172:173], v[172:173], 0, s[20:21]
	s_mov_b32 m0, s35
	ds_read_b128 v[194:197], v177
	ds_read_b128 v[198:201], v177 offset:1024
	ds_read_b128 v[202:205], v177 offset:2048
	ds_read_b128 v[228:231], v177 offset:3072
	global_load_lds_dwordx4 v[172:173], off
	v_lshl_add_u64 v[172:173], v[206:207], 0, s[20:21]
	s_add_i32 m0, s35, 0x2000
	s_nop 0
	global_load_lds_dwordx4 v[172:173], off
	s_barrier
	s_waitcnt lgkmcnt(0)
	s_setprio 1
	s_waitcnt lgkmcnt(0)
	v_mfma_f32_16x16x32_bf16 v[132:135], v[194:197], v[144:147], v[132:135]
	v_mfma_f32_16x16x32_bf16 v[128:131], v[202:205], v[144:147], v[128:131]
	v_mfma_f32_16x16x32_bf16 v[116:119], v[194:197], v[164:167], v[116:119]
	v_mfma_f32_16x16x32_bf16 v[112:115], v[202:205], v[164:167], v[112:115]
	v_mfma_f32_16x16x32_bf16 v[100:103], v[194:197], v[178:181], v[100:103]
	v_mfma_f32_16x16x32_bf16 v[96:99], v[202:205], v[178:181], v[96:99]
	v_mfma_f32_16x16x32_bf16 v[68:71], v[194:197], v[186:189], v[68:71]
	v_mfma_f32_16x16x32_bf16 v[64:67], v[202:205], v[186:189], v[64:67]
	v_mfma_f32_16x16x32_bf16 v[132:135], v[198:201], v[148:151], v[132:135]
	v_mfma_f32_16x16x32_bf16 v[128:131], v[228:231], v[148:151], v[128:131]
	v_mfma_f32_16x16x32_bf16 v[116:119], v[198:201], v[168:171], v[116:119]
	v_mfma_f32_16x16x32_bf16 v[112:115], v[228:231], v[168:171], v[112:115]
	v_mfma_f32_16x16x32_bf16 v[100:103], v[198:201], v[182:185], v[100:103]
	v_mfma_f32_16x16x32_bf16 v[96:99], v[228:231], v[182:185], v[96:99]
	v_mfma_f32_16x16x32_bf16 v[68:71], v[198:201], v[190:193], v[68:71]
	v_mfma_f32_16x16x32_bf16 v[64:67], v[228:231], v[190:193], v[64:67]
	s_setprio 0
	s_mov_b32 m0, s78
	v_lshl_add_u64 v[172:173], v[220:221], 0, s[20:21]
	s_barrier
	ds_read_b128 v[144:147], v175 offset:49152
	ds_read_b128 v[148:151], v175 offset:50176
	ds_read_b128 v[164:167], v175 offset:51200
	ds_read_b128 v[168:171], v175 offset:52224
	ds_read_b128 v[178:181], v175 offset:53248
	ds_read_b128 v[182:185], v175 offset:54272
	ds_read_b128 v[186:189], v175 offset:55296
	ds_read_b128 v[190:193], v175 offset:56320
	global_load_lds_dwordx4 v[172:173], off
	v_lshl_add_u64 v[172:173], v[232:233], 0, s[20:21]
	s_mov_b32 m0, s79
	s_nop 0
	global_load_lds_dwordx4 v[172:173], off
	s_barrier
; __device__ __forceinline__ float bflo(unsigned w) { return __uint_as_float(w << 16); }
; __device__ __forceinline__ float bfhi(unsigned w) { return __uint_as_float(w & 0xffff0000u); }
; __device__ __forceinline__ u32x4 pack8u(f32x4 a, f32x4 b) { u32x4 w = {cvt_pk_bf16(a[0], a[1]), cvt_pk_bf16(a[2], a[3]), cvt_pk_bf16(b[0], b[1]), cvt_pk_bf16(b[2], b[3])}; return w; }
; #define PG8_STAGE(bufoff, gbase, voff) do { _Pragma("unroll") for (int _i = 0; _i < 2; ++_i) \
;         __builtin_amdgcn_global_load_lds((const unsigned*)((const char*)(gbase) + (voff)[_i]), (LAS unsigned*)(lds + (bufoff) + ldsw + _i * 8192), 16, 0, 0); } while (0)
; #define PG8_WAIT_V(n) asm volatile("s_waitcnt vmcnt(" #n ")" ::: "memory")
; #define PG8_WAIT_L(n) asm volatile("s_waitcnt lgkmcnt(" #n ")" ::: "memory")
; template <class Epi>
; __device__ __forceinline__ void gemm_phase(LAS unsigned char* lds, const Gemm g, const Epi& E) {
;     ...
;             PG8_BAR; PG8_WAIT_L(0); PG8_MMA(1, 0, At, B0); PG8_BAR; PG8_SCHED;
;             PG8_STAGE(PG8_SB(1, 1), b3 + hstep, voffB);
;             PG8_WAIT_V(6); PG8_BAR; PG8_MMA(1, 1, At, B1); PG8_BAR;
;         }
;     __device__ __forceinline__ void operator()(const AccT& acc, const Unit& u, int wr, int wc, int fr, int fq) const {
;         const int b = (u.pm * 256) / SEQ;
;         f32x4 gt[2][2];
; #pragma unroll
;         for (int bj = 0; bj < 2; ++bj)
; #pragma unroll
;             for (int n = 0; n < 2; ++n) gt[bj][n] = *(const f32x4*)(GT + (size_t)b * 6 * D + u.pn * 256 + bj * 128 + wc * 32 + fq * 8 + 4 * n);
; #pragma unroll
;         for (int ai = 0; ai < 2; ++ai)
; #pragma unroll
;             for (int m = 0; m < 4; ++m) {
;                 const int row = u.pm * 256 + ai * 128 + wr * 64 + m * 16 + fr;
; #pragma unroll
;                 for (int bj = 0; bj < 2; ++bj) {
;                     const size_t off = (size_t)row * D + u.pn * 256 + bj * 128 + wc * 32 + fq * 8;
;                     f32x4 x0, x1;
;                     if (XINF) { x0 = *(const f32x4*)(XINF + off); x1 = *(const f32x4*)(XINF + off + 4); }
;                     else { const u32x4 w = *(const u32x4*)(XIN16 + off); x0 = (f32x4){bflo(w[0]), bfhi(w[0]), bflo(w[1]), bfhi(w[1])}; x1 = (f32x4){bflo(w[2]), bfhi(w[2]), bflo(w[3]), bfhi(w[3])}; }
;                     *(u32x4*)(XOUT + off) = pack8u(x0 + gt[bj][0] * acc[ai][bj][m][0], x1 + gt[bj][1] * acc[ai][bj][m][1]);
	s_waitcnt lgkmcnt(0)
	s_setprio 1
	s_waitcnt lgkmcnt(0)
	v_mfma_f32_16x16x32_bf16 v[60:63], v[72:75], v[144:147], v[60:63]
	v_mfma_f32_16x16x32_bf16 v[56:59], v[84:87], v[144:147], v[56:59]
	v_mfma_f32_16x16x32_bf16 v[44:47], v[72:75], v[164:167], v[44:47]
	v_mfma_f32_16x16x32_bf16 v[40:43], v[84:87], v[164:167], v[40:43]
	v_mfma_f32_16x16x32_bf16 v[28:31], v[72:75], v[178:181], v[28:31]
	v_mfma_f32_16x16x32_bf16 v[24:27], v[84:87], v[178:181], v[24:27]
	v_mfma_f32_16x16x32_bf16 v[12:15], v[72:75], v[186:189], v[12:15]
	v_mfma_f32_16x16x32_bf16 v[8:11], v[84:87], v[186:189], v[8:11]
	v_mfma_f32_16x16x32_bf16 v[60:63], v[76:79], v[148:151], v[60:63]
	v_mfma_f32_16x16x32_bf16 v[56:59], v[92:95], v[148:151], v[56:59]
	v_mfma_f32_16x16x32_bf16 v[44:47], v[76:79], v[168:171], v[44:47]
	v_mfma_f32_16x16x32_bf16 v[40:43], v[92:95], v[168:171], v[40:43]
	v_mfma_f32_16x16x32_bf16 v[28:31], v[76:79], v[182:185], v[28:31]
	v_mfma_f32_16x16x32_bf16 v[24:27], v[92:95], v[182:185], v[24:27]
	v_mfma_f32_16x16x32_bf16 v[12:15], v[76:79], v[190:193], v[12:15]
	v_mfma_f32_16x16x32_bf16 v[8:11], v[92:95], v[190:193], v[8:11]
	s_setprio 0
	s_barrier
	s_add_u32 s28, s28, 0x80080
	s_addc_u32 s29, s29, 0
	s_add_i32 s34, s34, s31
	v_lshl_add_u64 v[72:73], s[28:29], 0, v[208:209]
	s_mov_b32 m0, s34
	s_nop 0
	global_load_lds_dwordx4 v[72:73], off
	v_lshl_add_u64 v[72:73], s[28:29], 0, v[156:157]
	s_add_i32 m0, s34, 0x2000
	s_nop 0
	global_load_lds_dwordx4 v[72:73], off
	s_waitcnt vmcnt(6)
	s_barrier
	s_setprio 1
	v_mfma_f32_16x16x32_bf16 v[52:55], v[194:197], v[144:147], v[52:55]
	v_mfma_f32_16x16x32_bf16 v[48:51], v[202:205], v[144:147], v[48:51]
	v_mfma_f32_16x16x32_bf16 v[36:39], v[194:197], v[164:167], v[36:39]
	v_mfma_f32_16x16x32_bf16 v[32:35], v[202:205], v[164:167], v[32:35]
	v_mfma_f32_16x16x32_bf16 v[20:23], v[194:197], v[178:181], v[20:23]
	v_mfma_f32_16x16x32_bf16 v[16:19], v[202:205], v[178:181], v[16:19]
	v_mfma_f32_16x16x32_bf16 v[4:7], v[194:197], v[186:189], v[4:7]
	v_mfma_f32_16x16x32_bf16 v[0:3], v[202:205], v[186:189], v[0:3]
	v_mfma_f32_16x16x32_bf16 v[52:55], v[198:201], v[148:151], v[52:55]
	v_mfma_f32_16x16x32_bf16 v[48:51], v[228:231], v[148:151], v[48:51]
	v_mfma_f32_16x16x32_bf16 v[36:39], v[198:201], v[168:171], v[36:39]
	v_mfma_f32_16x16x32_bf16 v[32:35], v[228:231], v[168:171], v[32:35]
	v_mfma_f32_16x16x32_bf16 v[20:23], v[198:201], v[182:185], v[20:23]
	v_mfma_f32_16x16x32_bf16 v[16:19], v[228:231], v[182:185], v[16:19]
	v_mfma_f32_16x16x32_bf16 v[4:7], v[198:201], v[190:193], v[4:7]
	v_mfma_f32_16x16x32_bf16 v[0:3], v[228:231], v[190:193], v[0:3]
	s_setprio 0
	s_add_i32 vcc_lo, vcc_lo, 2
	s_add_u32 s26, s26, 0x100
	s_addc_u32 s27, s27, 0
	s_add_u32 s65, s65, 0x100
	s_addc_u32 s97, s97, 0
	s_cmp_gt_u32 vcc_lo, 29
	s_barrier
	s_cbranch_scc0 .LBB0_120
	s_ashr_i32 s26, s42, 31
	s_lshr_b32 s26, s26, 29
	s_add_i32 s26, s42, s26
	s_ashr_i32 s26, s26, 3
	s_mul_i32 s26, s26, 6
	s_ashr_i32 s27, s26, 31
	s_lshl_b64 s[26:27], s[26:27], 13
	s_add_u32 s34, s74, s26
	s_addc_u32 s35, s76, s27
	s_lshl_b32 s26, s96, 8
	s_ashr_i32 s27, s26, 31
	s_lshl_b64 s[28:29], s[26:27], 2
	s_add_u32 s28, s34, s28
	s_addc_u32 s29, s35, s29
	s_add_u32 s28, s28, s83
	s_addc_u32 s29, s29, 0
	global_load_dwordx4 v[84:87], v176, s[28:29] offset:16
	global_load_dwordx4 v[92:95], v176, s[28:29]
	global_load_dwordx4 v[72:75], v176, s[28:29] offset:528
	global_load_dwordx4 v[76:79], v176, s[28:29] offset:512
	v_readlane_b32 s34, v255, 22
	v_readlane_b32 s35, v255, 23
	v_lshl_add_u32 v166, s42, 8, v159
	v_or_b32_e32 v167, s26, v158
	v_lshlrev_b32_e32 v164, 2, v167
	v_lshl_add_u32 v164, v166, 13, v164
	v_lshlrev_b32_e32 v165, 1, v167
	v_lshl_add_u32 v165, v166, 12, v165
	s_and_b64 vcc, exec, s[44:45]
	s_cbranch_vccnz .Lepr1_f32
	v_add_u32_e32 v166, 0x0, v165
	global_load_dwordx4 v[168:171], v166, s[34:35] offset:0
	v_add_u32_e32 v166, 0x0, v165
	global_load_dwordx4 v[178:181], v166, s[34:35] offset:256
	v_add_u32_e32 v166, 0x10000, v165
	global_load_dwordx4 v[182:185], v166, s[34:35] offset:0
	v_add_u32_e32 v166, 0x10000, v165
	global_load_dwordx4 v[186:189], v166, s[34:35] offset:256
	v_add_u32_e32 v166, 0x20000, v165
	global_load_dwordx4 v[190:193], v166, s[34:35] offset:0
	v_add_u32_e32 v166, 0x20000, v165
	global_load_dwordx4 v[194:197], v166, s[34:35] offset:256
	v_add_u32_e32 v166, 0x30000, v165
	global_load_dwordx4 v[198:201], v166, s[34:35] offset:0
	v_add_u32_e32 v166, 0x30000, v165
	global_load_dwordx4 v[202:205], v166, s[34:35] offset:256
	v_add_u32_e32 v166, 0x80000, v165
	global_load_dwordx4 v[228:231], v166, s[34:35] offset:0
	s_waitcnt vmcnt(8)
	v_lshlrev_b32_e32 v144, 16, v168
	v_and_b32_e32 v145, 0xffff0000, v168
	v_lshlrev_b32_e32 v146, 16, v169
	v_and_b32_e32 v147, 0xffff0000, v169
	v_lshlrev_b32_e32 v148, 16, v170
	v_and_b32_e32 v149, 0xffff0000, v170
	v_lshlrev_b32_e32 v150, 16, v171
	v_and_b32_e32 v151, 0xffff0000, v171
	v_pk_fma_f32 v[140:141], v[140:141], v[92:93], v[144:145]
	v_pk_fma_f32 v[142:143], v[142:143], v[94:95], v[146:147]
	v_pk_fma_f32 v[136:137], v[136:137], v[84:85], v[148:149]
	v_pk_fma_f32 v[138:139], v[138:139], v[86:87], v[150:151]
	v_cvt_pk_bf16_f32 v140, v140, v141
	v_cvt_pk_bf16_f32 v141, v142, v143
	v_cvt_pk_bf16_f32 v142, v136, v137
	v_cvt_pk_bf16_f32 v143, v138, v139
	v_add_u32_e32 v167, 0x0, v165
	global_store_dwordx4 v167, v[140:143], s[34:35] offset:0
	v_add_u32_e32 v166, 0x80000, v165
	global_load_dwordx4 v[168:171], v166, s[34:35] offset:256
	v_add_u32_e32 v166, 0x90000, v165
	global_load_dwordx4 v[136:139], v166, s[34:35] offset:0
	s_waitcnt vmcnt(10)
; __device__ __forceinline__ float bflo(unsigned w) { return __uint_as_float(w << 16); }
; __device__ __forceinline__ float bfhi(unsigned w) { return __uint_as_float(w & 0xffff0000u); }
; __device__ __forceinline__ u32x4 pack8u(f32x4 a, f32x4 b) { u32x4 w = {cvt_pk_bf16(a[0], a[1]), cvt_pk_bf16(a[2], a[3]), cvt_pk_bf16(b[0], b[1]), cvt_pk_bf16(b[2], b[3])}; return w; }
;     __device__ __forceinline__ void operator()(const AccT& acc, const Unit& u, int wr, int wc, int fr, int fq) const {
;     ...
;         for (int ai = 0; ai < 2; ++ai)
; #pragma unroll
;             for (int m = 0; m < 4; ++m) {
;                 const int row = u.pm * 256 + ai * 128 + wr * 64 + m * 16 + fr;
; #pragma unroll
;                 for (int bj = 0; bj < 2; ++bj) {
;                     const size_t off = (size_t)row * D + u.pn * 256 + bj * 128 + wc * 32 + fq * 8;
;                     f32x4 x0, x1;
;                     if (XINF) { x0 = *(const f32x4*)(XINF + off); x1 = *(const f32x4*)(XINF + off + 4); }
;                     else { const u32x4 w = *(const u32x4*)(XIN16 + off); x0 = (f32x4){bflo(w[0]), bfhi(w[0]), bflo(w[1]), bfhi(w[1])}; x1 = (f32x4){bflo(w[2]), bfhi(w[2]), bflo(w[3]), bfhi(w[3])}; }
;                     *(u32x4*)(XOUT + off) = pack8u(x0 + gt[bj][0] * acc[ai][bj][m][0], x1 + gt[bj][1] * acc[ai][bj][m][1]);
;                 }
	v_lshlrev_b32_e32 v144, 16, v178
	v_and_b32_e32 v145, 0xffff0000, v178
	v_lshlrev_b32_e32 v146, 16, v179
	v_and_b32_e32 v147, 0xffff0000, v179
	v_lshlrev_b32_e32 v148, 16, v180
	v_and_b32_e32 v149, 0xffff0000, v180
	v_lshlrev_b32_e32 v150, 16, v181
	v_and_b32_e32 v151, 0xffff0000, v181
	v_pk_fma_f32 v[132:133], v[132:133], v[76:77], v[144:145]
	v_pk_fma_f32 v[134:135], v[134:135], v[78:79], v[146:147]
	v_pk_fma_f32 v[128:129], v[128:129], v[72:73], v[148:149]
	v_pk_fma_f32 v[130:131], v[130:131], v[74:75], v[150:151]
	v_cvt_pk_bf16_f32 v132, v132, v133
	v_cvt_pk_bf16_f32 v133, v134, v135
	v_cvt_pk_bf16_f32 v134, v128, v129
	v_cvt_pk_bf16_f32 v135, v130, v131
	v_add_u32_e32 v167, 0x0, v165
	global_store_dwordx4 v167, v[132:135], s[34:35] offset:256
	v_add_u32_e32 v166, 0x90000, v165
	global_load_dwordx4 v[178:181], v166, s[34:35] offset:256
	v_add_u32_e32 v166, 0xa0000, v165
	global_load_dwordx4 v[128:131], v166, s[34:35] offset:0
	s_waitcnt vmcnt(12)
	v_lshlrev_b32_e32 v144, 16, v182
	v_and_b32_e32 v145, 0xffff0000, v182
	v_lshlrev_b32_e32 v146, 16, v183
	v_and_b32_e32 v147, 0xffff0000, v183
	v_lshlrev_b32_e32 v148, 16, v184
	v_and_b32_e32 v149, 0xffff0000, v184
	v_lshlrev_b32_e32 v150, 16, v185
	v_and_b32_e32 v151, 0xffff0000, v185
	v_pk_fma_f32 v[124:125], v[124:125], v[92:93], v[144:145]
	v_pk_fma_f32 v[126:127], v[126:127], v[94:95], v[146:147]
	v_pk_fma_f32 v[120:121], v[120:121], v[84:85], v[148:149]
	v_pk_fma_f32 v[122:123], v[122:123], v[86:87], v[150:151]
	v_cvt_pk_bf16_f32 v124, v124, v125
	v_cvt_pk_bf16_f32 v125, v126, v127
	v_cvt_pk_bf16_f32 v126, v120, v121
	v_cvt_pk_bf16_f32 v127, v122, v123
	v_add_u32_e32 v167, 0x10000, v165
	global_store_dwordx4 v167, v[124:127], s[34:35] offset:0
	v_add_u32_e32 v166, 0xa0000, v165
	global_load_dwordx4 v[182:185], v166, s[34:35] offset:256
	v_add_u32_e32 v166, 0xb0000, v165
	global_load_dwordx4 v[120:123], v166, s[34:35] offset:0
	s_waitcnt vmcnt(14)
	v_lshlrev_b32_e32 v144, 16, v186
	v_and_b32_e32 v145, 0xffff0000, v186
	v_lshlrev_b32_e32 v146, 16, v187
	v_and_b32_e32 v147, 0xffff0000, v187
	v_lshlrev_b32_e32 v148, 16, v188
	v_and_b32_e32 v149, 0xffff0000, v188
	v_lshlrev_b32_e32 v150, 16, v189
	v_and_b32_e32 v151, 0xffff0000, v189
	v_pk_fma_f32 v[116:117], v[116:117], v[76:77], v[144:145]
	v_pk_fma_f32 v[118:119], v[118:119], v[78:79], v[146:147]
	v_pk_fma_f32 v[112:113], v[112:113], v[72:73], v[148:149]
	v_pk_fma_f32 v[114:115], v[114:115], v[74:75], v[150:151]
	v_cvt_pk_bf16_f32 v116, v116, v117
	v_cvt_pk_bf16_f32 v117, v118, v119
	v_cvt_pk_bf16_f32 v118, v112, v113
	v_cvt_pk_bf16_f32 v119, v114, v115
	v_add_u32_e32 v167, 0x10000, v165
	global_store_dwordx4 v167, v[116:119], s[34:35] offset:256
	v_add_u32_e32 v166, 0xb0000, v165
	global_load_dwordx4 v[186:189], v166, s[34:35] offset:256
	s_waitcnt vmcnt(15)
	v_lshlrev_b32_e32 v144, 16, v190
	v_and_b32_e32 v145, 0xffff0000, v190
	v_lshlrev_b32_e32 v146, 16, v191
	v_and_b32_e32 v147, 0xffff0000, v191
	v_lshlrev_b32_e32 v148, 16, v192
	v_and_b32_e32 v149, 0xffff0000, v192
	v_lshlrev_b32_e32 v150, 16, v193
	v_and_b32_e32 v151, 0xffff0000, v193
	v_pk_fma_f32 v[108:109], v[108:109], v[92:93], v[144:145]
	v_pk_fma_f32 v[110:111], v[110:111], v[94:95], v[146:147]
	v_pk_fma_f32 v[104:105], v[104:105], v[84:85], v[148:149]
	v_pk_fma_f32 v[106:107], v[106:107], v[86:87], v[150:151]
	v_cvt_pk_bf16_f32 v108, v108, v109
	v_cvt_pk_bf16_f32 v109, v110, v111
	v_cvt_pk_bf16_f32 v110, v104, v105
	v_cvt_pk_bf16_f32 v111, v106, v107
	v_add_u32_e32 v167, 0x20000, v165
	global_store_dwordx4 v167, v[108:111], s[34:35] offset:0
	s_waitcnt vmcnt(15)
	v_lshlrev_b32_e32 v144, 16, v194
	v_and_b32_e32 v145, 0xffff0000, v194
	v_lshlrev_b32_e32 v146, 16, v195
	v_and_b32_e32 v147, 0xffff0000, v195
	v_lshlrev_b32_e32 v148, 16, v196
	v_and_b32_e32 v149, 0xffff0000, v196
	v_lshlrev_b32_e32 v150, 16, v197
	v_and_b32_e32 v151, 0xffff0000, v197
	v_pk_fma_f32 v[100:101], v[100:101], v[76:77], v[144:145]
	v_pk_fma_f32 v[102:103], v[102:103], v[78:79], v[146:147]
	v_pk_fma_f32 v[96:97], v[96:97], v[72:73], v[148:149]
	v_pk_fma_f32 v[98:99], v[98:99], v[74:75], v[150:151]
	v_cvt_pk_bf16_f32 v100, v100, v101
	v_cvt_pk_bf16_f32 v101, v102, v103
	v_cvt_pk_bf16_f32 v102, v96, v97
	v_cvt_pk_bf16_f32 v103, v98, v99
	v_add_u32_e32 v167, 0x20000, v165
	global_store_dwordx4 v167, v[100:103], s[34:35] offset:256
	s_waitcnt vmcnt(15)
	v_lshlrev_b32_e32 v144, 16, v198
	v_and_b32_e32 v145, 0xffff0000, v198
	v_lshlrev_b32_e32 v146, 16, v199
	v_and_b32_e32 v147, 0xffff0000, v199
	v_lshlrev_b32_e32 v148, 16, v200
	v_and_b32_e32 v149, 0xffff0000, v200
	v_lshlrev_b32_e32 v150, 16, v201
	v_and_b32_e32 v151, 0xffff0000, v201
	v_pk_fma_f32 v[88:89], v[88:89], v[92:93], v[144:145]
	v_pk_fma_f32 v[90:91], v[90:91], v[94:95], v[146:147]
	v_pk_fma_f32 v[80:81], v[80:81], v[84:85], v[148:149]
	v_pk_fma_f32 v[82:83], v[82:83], v[86:87], v[150:151]
	v_cvt_pk_bf16_f32 v88, v88, v89
	v_cvt_pk_bf16_f32 v89, v90, v91
	v_cvt_pk_bf16_f32 v90, v80, v81
	v_cvt_pk_bf16_f32 v91, v82, v83
	v_add_u32_e32 v167, 0x30000, v165
	global_store_dwordx4 v167, v[88:91], s[34:35] offset:0
	s_waitcnt vmcnt(15)
	v_lshlrev_b32_e32 v144, 16, v202
	v_and_b32_e32 v145, 0xffff0000, v202
	v_lshlrev_b32_e32 v146, 16, v203
	v_and_b32_e32 v147, 0xffff0000, v203
	v_lshlrev_b32_e32 v148, 16, v204
	v_and_b32_e32 v149, 0xffff0000, v204
	v_lshlrev_b32_e32 v150, 16, v205
	v_and_b32_e32 v151, 0xffff0000, v205
	v_pk_fma_f32 v[68:69], v[68:69], v[76:77], v[144:145]
	v_pk_fma_f32 v[70:71], v[70:71], v[78:79], v[146:147]
	v_pk_fma_f32 v[64:65], v[64:65], v[72:73], v[148:149]
	v_pk_fma_f32 v[66:67], v[66:67], v[74:75], v[150:151]
	v_cvt_pk_bf16_f32 v68, v68, v69
	v_cvt_pk_bf16_f32 v69, v70, v71
	v_cvt_pk_bf16_f32 v70, v64, v65
	v_cvt_pk_bf16_f32 v71, v66, v67
	v_add_u32_e32 v167, 0x30000, v165
	global_store_dwordx4 v167, v[68:71], s[34:35] offset:256
	s_waitcnt vmcnt(15)
; __device__ __forceinline__ float bflo(unsigned w) { return __uint_as_float(w << 16); }
; __device__ __forceinline__ float bfhi(unsigned w) { return __uint_as_float(w & 0xffff0000u); }
; __device__ __forceinline__ u32x4 pack8u(f32x4 a, f32x4 b) { u32x4 w = {cvt_pk_bf16(a[0], a[1]), cvt_pk_bf16(a[2], a[3]), cvt_pk_bf16(b[0], b[1]), cvt_pk_bf16(b[2], b[3])}; return w; }
;     __device__ __forceinline__ void operator()(const AccT& acc, const Unit& u, int wr, int wc, int fr, int fq) const {
;     ...
;         for (int ai = 0; ai < 2; ++ai)
; #pragma unroll
;             for (int m = 0; m < 4; ++m) {
;                 const int row = u.pm * 256 + ai * 128 + wr * 64 + m * 16 + fr;
; #pragma unroll
;                 for (int bj = 0; bj < 2; ++bj) {
;                     const size_t off = (size_t)row * D + u.pn * 256 + bj * 128 + wc * 32 + fq * 8;
;                     f32x4 x0, x1;
;                     if (XINF) { x0 = *(const f32x4*)(XINF + off); x1 = *(const f32x4*)(XINF + off + 4); }
;                     else { const u32x4 w = *(const u32x4*)(XIN16 + off); x0 = (f32x4){bflo(w[0]), bfhi(w[0]), bflo(w[1]), bfhi(w[1])}; x1 = (f32x4){bflo(w[2]), bfhi(w[2]), bflo(w[3]), bfhi(w[3])}; }
;                     *(u32x4*)(XOUT + off) = pack8u(x0 + gt[bj][0] * acc[ai][bj][m][0], x1 + gt[bj][1] * acc[ai][bj][m][1]);
;                 }
	v_lshlrev_b32_e32 v144, 16, v228
	v_and_b32_e32 v145, 0xffff0000, v228
	v_lshlrev_b32_e32 v146, 16, v229
	v_and_b32_e32 v147, 0xffff0000, v229
	v_lshlrev_b32_e32 v148, 16, v230
	v_and_b32_e32 v149, 0xffff0000, v230
	v_lshlrev_b32_e32 v150, 16, v231
	v_and_b32_e32 v151, 0xffff0000, v231
	v_pk_fma_f32 v[60:61], v[60:61], v[92:93], v[144:145]
	v_pk_fma_f32 v[62:63], v[62:63], v[94:95], v[146:147]
	v_pk_fma_f32 v[56:57], v[56:57], v[84:85], v[148:149]
	v_pk_fma_f32 v[58:59], v[58:59], v[86:87], v[150:151]
	v_cvt_pk_bf16_f32 v60, v60, v61
	v_cvt_pk_bf16_f32 v61, v62, v63
	v_cvt_pk_bf16_f32 v62, v56, v57
	v_cvt_pk_bf16_f32 v63, v58, v59
	v_add_u32_e32 v167, 0x80000, v165
	global_store_dwordx4 v167, v[60:63], s[34:35] offset:0
	s_waitcnt vmcnt(14)
	v_lshlrev_b32_e32 v144, 16, v168
	v_and_b32_e32 v145, 0xffff0000, v168
	v_lshlrev_b32_e32 v146, 16, v169
	v_and_b32_e32 v147, 0xffff0000, v169
	v_lshlrev_b32_e32 v148, 16, v170
	v_and_b32_e32 v149, 0xffff0000, v170
	v_lshlrev_b32_e32 v150, 16, v171
	v_and_b32_e32 v151, 0xffff0000, v171
	v_pk_fma_f32 v[52:53], v[52:53], v[76:77], v[144:145]
	v_pk_fma_f32 v[54:55], v[54:55], v[78:79], v[146:147]
	v_pk_fma_f32 v[48:49], v[48:49], v[72:73], v[148:149]
	v_pk_fma_f32 v[50:51], v[50:51], v[74:75], v[150:151]
	v_cvt_pk_bf16_f32 v52, v52, v53
	v_cvt_pk_bf16_f32 v53, v54, v55
	v_cvt_pk_bf16_f32 v54, v48, v49
	v_cvt_pk_bf16_f32 v55, v50, v51
	v_add_u32_e32 v167, 0x80000, v165
	global_store_dwordx4 v167, v[52:55], s[34:35] offset:256
	s_waitcnt vmcnt(14)
	v_lshlrev_b32_e32 v144, 16, v136
	v_and_b32_e32 v145, 0xffff0000, v136
	v_lshlrev_b32_e32 v146, 16, v137
	v_and_b32_e32 v147, 0xffff0000, v137
	v_lshlrev_b32_e32 v148, 16, v138
	v_and_b32_e32 v149, 0xffff0000, v138
	v_lshlrev_b32_e32 v150, 16, v139
	v_and_b32_e32 v151, 0xffff0000, v139
	v_pk_fma_f32 v[44:45], v[44:45], v[92:93], v[144:145]
	v_pk_fma_f32 v[46:47], v[46:47], v[94:95], v[146:147]
	v_pk_fma_f32 v[40:41], v[40:41], v[84:85], v[148:149]
	v_pk_fma_f32 v[42:43], v[42:43], v[86:87], v[150:151]
	v_cvt_pk_bf16_f32 v44, v44, v45
	v_cvt_pk_bf16_f32 v45, v46, v47
	v_cvt_pk_bf16_f32 v46, v40, v41
	v_cvt_pk_bf16_f32 v47, v42, v43
	v_add_u32_e32 v167, 0x90000, v165
	global_store_dwordx4 v167, v[44:47], s[34:35] offset:0
	s_waitcnt vmcnt(13)
	v_lshlrev_b32_e32 v144, 16, v178
	v_and_b32_e32 v145, 0xffff0000, v178
	v_lshlrev_b32_e32 v146, 16, v179
	v_and_b32_e32 v147, 0xffff0000, v179
	v_lshlrev_b32_e32 v148, 16, v180
	v_and_b32_e32 v149, 0xffff0000, v180
	v_lshlrev_b32_e32 v150, 16, v181
	v_and_b32_e32 v151, 0xffff0000, v181
	v_pk_fma_f32 v[36:37], v[36:37], v[76:77], v[144:145]
	v_pk_fma_f32 v[38:39], v[38:39], v[78:79], v[146:147]
	v_pk_fma_f32 v[32:33], v[32:33], v[72:73], v[148:149]
	v_pk_fma_f32 v[34:35], v[34:35], v[74:75], v[150:151]
	v_cvt_pk_bf16_f32 v36, v36, v37
	v_cvt_pk_bf16_f32 v37, v38, v39
	v_cvt_pk_bf16_f32 v38, v32, v33
	v_cvt_pk_bf16_f32 v39, v34, v35
	v_add_u32_e32 v167, 0x90000, v165
	global_store_dwordx4 v167, v[36:39], s[34:35] offset:256
	s_waitcnt vmcnt(13)
	v_lshlrev_b32_e32 v144, 16, v128
	v_and_b32_e32 v145, 0xffff0000, v128
	v_lshlrev_b32_e32 v146, 16, v129
	v_and_b32_e32 v147, 0xffff0000, v129
	v_lshlrev_b32_e32 v148, 16, v130
	v_and_b32_e32 v149, 0xffff0000, v130
	v_lshlrev_b32_e32 v150, 16, v131
	v_and_b32_e32 v151, 0xffff0000, v131
	v_pk_fma_f32 v[28:29], v[28:29], v[92:93], v[144:145]
	v_pk_fma_f32 v[30:31], v[30:31], v[94:95], v[146:147]
	v_pk_fma_f32 v[24:25], v[24:25], v[84:85], v[148:149]
	v_pk_fma_f32 v[26:27], v[26:27], v[86:87], v[150:151]
	v_cvt_pk_bf16_f32 v28, v28, v29
	v_cvt_pk_bf16_f32 v29, v30, v31
	v_cvt_pk_bf16_f32 v30, v24, v25
	v_cvt_pk_bf16_f32 v31, v26, v27
	v_add_u32_e32 v167, 0xa0000, v165
	global_store_dwordx4 v167, v[28:31], s[34:35] offset:0
	s_waitcnt vmcnt(12)
	v_lshlrev_b32_e32 v144, 16, v182
	v_and_b32_e32 v145, 0xffff0000, v182
	v_lshlrev_b32_e32 v146, 16, v183
	v_and_b32_e32 v147, 0xffff0000, v183
	v_lshlrev_b32_e32 v148, 16, v184
	v_and_b32_e32 v149, 0xffff0000, v184
	v_lshlrev_b32_e32 v150, 16, v185
	v_and_b32_e32 v151, 0xffff0000, v185
	v_pk_fma_f32 v[20:21], v[20:21], v[76:77], v[144:145]
	v_pk_fma_f32 v[22:23], v[22:23], v[78:79], v[146:147]
	v_pk_fma_f32 v[16:17], v[16:17], v[72:73], v[148:149]
	v_pk_fma_f32 v[18:19], v[18:19], v[74:75], v[150:151]
	v_cvt_pk_bf16_f32 v20, v20, v21
	v_cvt_pk_bf16_f32 v21, v22, v23
	v_cvt_pk_bf16_f32 v22, v16, v17
	v_cvt_pk_bf16_f32 v23, v18, v19
	v_add_u32_e32 v167, 0xa0000, v165
	global_store_dwordx4 v167, v[20:23], s[34:35] offset:256
	s_waitcnt vmcnt(12)
	v_lshlrev_b32_e32 v144, 16, v120
	v_and_b32_e32 v145, 0xffff0000, v120
	v_lshlrev_b32_e32 v146, 16, v121
	v_and_b32_e32 v147, 0xffff0000, v121
	v_lshlrev_b32_e32 v148, 16, v122
	v_and_b32_e32 v149, 0xffff0000, v122
	v_lshlrev_b32_e32 v150, 16, v123
	v_and_b32_e32 v151, 0xffff0000, v123
	v_pk_fma_f32 v[12:13], v[12:13], v[92:93], v[144:145]
	v_pk_fma_f32 v[14:15], v[14:15], v[94:95], v[146:147]
	v_pk_fma_f32 v[8:9], v[8:9], v[84:85], v[148:149]
	v_pk_fma_f32 v[10:11], v[10:11], v[86:87], v[150:151]
	v_cvt_pk_bf16_f32 v12, v12, v13
	v_cvt_pk_bf16_f32 v13, v14, v15
	v_cvt_pk_bf16_f32 v14, v8, v9
	v_cvt_pk_bf16_f32 v15, v10, v11
	v_add_u32_e32 v167, 0xb0000, v165
	global_store_dwordx4 v167, v[12:15], s[34:35] offset:0
	s_waitcnt vmcnt(11)
	v_lshlrev_b32_e32 v144, 16, v186
	v_and_b32_e32 v145, 0xffff0000, v186
	v_lshlrev_b32_e32 v146, 16, v187
	v_and_b32_e32 v147, 0xffff0000, v187
	v_lshlrev_b32_e32 v148, 16, v188
	v_and_b32_e32 v149, 0xffff0000, v188
	v_lshlrev_b32_e32 v150, 16, v189
	v_and_b32_e32 v151, 0xffff0000, v189
	v_pk_fma_f32 v[4:5], v[4:5], v[76:77], v[144:145]
	v_pk_fma_f32 v[6:7], v[6:7], v[78:79], v[146:147]
	v_pk_fma_f32 v[0:1], v[0:1], v[72:73], v[148:149]
	v_pk_fma_f32 v[2:3], v[2:3], v[74:75], v[150:151]
	v_cvt_pk_bf16_f32 v4, v4, v5
	v_cvt_pk_bf16_f32 v5, v6, v7
	v_cvt_pk_bf16_f32 v6, v0, v1
	v_cvt_pk_bf16_f32 v7, v2, v3
	v_add_u32_e32 v167, 0xb0000, v165
	global_store_dwordx4 v167, v[4:7], s[34:35] offset:256
	s_mov_b64 s[42:43], exec
	s_branch .Lepr1_latch
; __device__ __forceinline__ float bflo(unsigned w) { return __uint_as_float(w << 16); }
; __device__ __forceinline__ float bfhi(unsigned w) { return __uint_as_float(w & 0xffff0000u); }
; __device__ __forceinline__ u32x4 pack8u(f32x4 a, f32x4 b) { u32x4 w = {cvt_pk_bf16(a[0], a[1]), cvt_pk_bf16(a[2], a[3]), cvt_pk_bf16(b[0], b[1]), cvt_pk_bf16(b[2], b[3])}; return w; }
;     __device__ __forceinline__ void operator()(const AccT& acc, const Unit& u, int wr, int wc, int fr, int fq) const {
;     ...
;                     if (XINF) { x0 = *(const f32x4*)(XINF + off); x1 = *(const f32x4*)(XINF + off + 4); }
;                     else { const u32x4 w = *(const u32x4*)(XIN16 + off); x0 = (f32x4){bflo(w[0]), bfhi(w[0]), bflo(w[1]), bfhi(w[1])}; x1 = (f32x4){bflo(w[2]), bfhi(w[2]), bflo(w[3]), bfhi(w[3])}; }
;                     *(u32x4*)(XOUT + off) = pack8u(x0 + gt[bj][0] * acc[ai][bj][m][0], x1 + gt[bj][1] * acc[ai][bj][m][1]);
.Lepr1_f32:
	v_add_u32_e32 v166, 0x0, v164
	global_load_dwordx4 v[168:171], v166, s[0:1] offset:0
	global_load_dwordx4 v[178:181], v166, s[0:1] offset:16
	v_add_u32_e32 v166, 0x0, v164
	global_load_dwordx4 v[182:185], v166, s[0:1] offset:512
	global_load_dwordx4 v[186:189], v166, s[0:1] offset:528
	v_add_u32_e32 v166, 0x20000, v164
	global_load_dwordx4 v[190:193], v166, s[0:1] offset:0
	global_load_dwordx4 v[194:197], v166, s[0:1] offset:16
	v_add_u32_e32 v166, 0x20000, v164
	global_load_dwordx4 v[198:201], v166, s[0:1] offset:512
	global_load_dwordx4 v[202:205], v166, s[0:1] offset:528
	s_waitcnt vmcnt(6)
	v_pk_fma_f32 v[140:141], v[140:141], v[92:93], v[168:169]
	v_pk_fma_f32 v[142:143], v[142:143], v[94:95], v[170:171]
	v_pk_fma_f32 v[136:137], v[136:137], v[84:85], v[178:179]
	v_pk_fma_f32 v[138:139], v[138:139], v[86:87], v[180:181]
	v_cvt_pk_bf16_f32 v140, v140, v141
	v_cvt_pk_bf16_f32 v141, v142, v143
	v_cvt_pk_bf16_f32 v142, v136, v137
	v_cvt_pk_bf16_f32 v143, v138, v139
	v_add_u32_e32 v167, 0x0, v165
	global_store_dwordx4 v167, v[140:143], s[34:35] offset:0
	v_add_u32_e32 v166, 0x40000, v164
	global_load_dwordx4 v[228:231], v166, s[0:1] offset:0
	global_load_dwordx4 v[168:171], v166, s[0:1] offset:16
	v_add_u32_e32 v166, 0x40000, v164
	global_load_dwordx4 v[178:181], v166, s[0:1] offset:512
	global_load_dwordx4 v[136:139], v166, s[0:1] offset:528
	s_waitcnt vmcnt(9)
	v_pk_fma_f32 v[132:133], v[132:133], v[76:77], v[182:183]
	v_pk_fma_f32 v[134:135], v[134:135], v[78:79], v[184:185]
	v_pk_fma_f32 v[128:129], v[128:129], v[72:73], v[186:187]
	v_pk_fma_f32 v[130:131], v[130:131], v[74:75], v[188:189]
	v_cvt_pk_bf16_f32 v132, v132, v133
	v_cvt_pk_bf16_f32 v133, v134, v135
	v_cvt_pk_bf16_f32 v134, v128, v129
	v_cvt_pk_bf16_f32 v135, v130, v131
	v_add_u32_e32 v167, 0x0, v165
	global_store_dwordx4 v167, v[132:135], s[34:35] offset:256
	v_add_u32_e32 v166, 0x60000, v164
	global_load_dwordx4 v[182:185], v166, s[0:1] offset:0
	global_load_dwordx4 v[186:189], v166, s[0:1] offset:16
	s_waitcnt vmcnt(10)
	v_pk_fma_f32 v[124:125], v[124:125], v[92:93], v[190:191]
	v_pk_fma_f32 v[126:127], v[126:127], v[94:95], v[192:193]
	v_pk_fma_f32 v[120:121], v[120:121], v[84:85], v[194:195]
	v_pk_fma_f32 v[122:123], v[122:123], v[86:87], v[196:197]
	v_cvt_pk_bf16_f32 v124, v124, v125
	v_cvt_pk_bf16_f32 v125, v126, v127
	v_cvt_pk_bf16_f32 v126, v120, v121
	v_cvt_pk_bf16_f32 v127, v122, v123
	v_add_u32_e32 v167, 0x10000, v165
	global_store_dwordx4 v167, v[124:127], s[34:35] offset:0
	v_add_u32_e32 v166, 0x60000, v164
	global_load_dwordx4 v[128:131], v166, s[0:1] offset:512
	global_load_dwordx4 v[190:193], v166, s[0:1] offset:528
	v_add_u32_e32 v166, 0x100000, v164
	global_load_dwordx4 v[194:197], v166, s[0:1] offset:0
	global_load_dwordx4 v[120:123], v166, s[0:1] offset:16
	s_waitcnt vmcnt(13)
	v_pk_fma_f32 v[116:117], v[116:117], v[76:77], v[198:199]
	v_pk_fma_f32 v[118:119], v[118:119], v[78:79], v[200:201]
	v_pk_fma_f32 v[112:113], v[112:113], v[72:73], v[202:203]
	v_pk_fma_f32 v[114:115], v[114:115], v[74:75], v[204:205]
	v_cvt_pk_bf16_f32 v116, v116, v117
	v_cvt_pk_bf16_f32 v117, v118, v119
	v_cvt_pk_bf16_f32 v118, v112, v113
	v_cvt_pk_bf16_f32 v119, v114, v115
	v_add_u32_e32 v167, 0x10000, v165
	global_store_dwordx4 v167, v[116:119], s[34:35] offset:256
	v_add_u32_e32 v166, 0x100000, v164
	global_load_dwordx4 v[198:201], v166, s[0:1] offset:512
	global_load_dwordx4 v[202:205], v166, s[0:1] offset:528
	s_waitcnt vmcnt(13)
	v_pk_fma_f32 v[108:109], v[108:109], v[92:93], v[228:229]
	v_pk_fma_f32 v[110:111], v[110:111], v[94:95], v[230:231]
	v_pk_fma_f32 v[104:105], v[104:105], v[84:85], v[168:169]
	v_pk_fma_f32 v[106:107], v[106:107], v[86:87], v[170:171]
	v_cvt_pk_bf16_f32 v108, v108, v109
	v_cvt_pk_bf16_f32 v109, v110, v111
	v_cvt_pk_bf16_f32 v110, v104, v105
	v_cvt_pk_bf16_f32 v111, v106, v107
	v_add_u32_e32 v167, 0x20000, v165
	global_store_dwordx4 v167, v[108:111], s[34:35] offset:0
	v_add_u32_e32 v166, 0x120000, v164
	global_load_dwordx4 v[112:115], v166, s[0:1] offset:0
	global_load_dwordx4 v[228:231], v166, s[0:1] offset:16
	v_add_u32_e32 v166, 0x120000, v164
	global_load_dwordx4 v[168:171], v166, s[0:1] offset:512
	global_load_dwordx4 v[104:107], v166, s[0:1] offset:528
	s_waitcnt vmcnt(16)
	v_pk_fma_f32 v[100:101], v[100:101], v[76:77], v[178:179]
	v_pk_fma_f32 v[102:103], v[102:103], v[78:79], v[180:181]
	v_pk_fma_f32 v[96:97], v[96:97], v[72:73], v[136:137]
	v_pk_fma_f32 v[98:99], v[98:99], v[74:75], v[138:139]
	v_cvt_pk_bf16_f32 v100, v100, v101
	v_cvt_pk_bf16_f32 v101, v102, v103
	v_cvt_pk_bf16_f32 v102, v96, v97
	v_cvt_pk_bf16_f32 v103, v98, v99
	v_add_u32_e32 v167, 0x20000, v165
	global_store_dwordx4 v167, v[100:103], s[34:35] offset:256
	v_add_u32_e32 v166, 0x140000, v164
	global_load_dwordx4 v[178:181], v166, s[0:1] offset:0
	global_load_dwordx4 v[136:139], v166, s[0:1] offset:16
	s_waitcnt vmcnt(16)
; __device__ __forceinline__ float bflo(unsigned w) { return __uint_as_float(w << 16); }
; __device__ __forceinline__ float bfhi(unsigned w) { return __uint_as_float(w & 0xffff0000u); }
; __device__ __forceinline__ u32x4 pack8u(f32x4 a, f32x4 b) { u32x4 w = {cvt_pk_bf16(a[0], a[1]), cvt_pk_bf16(a[2], a[3]), cvt_pk_bf16(b[0], b[1]), cvt_pk_bf16(b[2], b[3])}; return w; }
;     __device__ __forceinline__ void operator()(const AccT& acc, const Unit& u, int wr, int wc, int fr, int fq) const {
;     ...
;                     if (XINF) { x0 = *(const f32x4*)(XINF + off); x1 = *(const f32x4*)(XINF + off + 4); }
;                     else { const u32x4 w = *(const u32x4*)(XIN16 + off); x0 = (f32x4){bflo(w[0]), bfhi(w[0]), bflo(w[1]), bfhi(w[1])}; x1 = (f32x4){bflo(w[2]), bfhi(w[2]), bflo(w[3]), bfhi(w[3])}; }
;                     *(u32x4*)(XOUT + off) = pack8u(x0 + gt[bj][0] * acc[ai][bj][m][0], x1 + gt[bj][1] * acc[ai][bj][m][1]);
	v_pk_fma_f32 v[88:89], v[88:89], v[92:93], v[182:183]
	v_pk_fma_f32 v[90:91], v[90:91], v[94:95], v[184:185]
	v_pk_fma_f32 v[80:81], v[80:81], v[84:85], v[186:187]
	v_pk_fma_f32 v[82:83], v[82:83], v[86:87], v[188:189]
	v_cvt_pk_bf16_f32 v88, v88, v89
	v_cvt_pk_bf16_f32 v89, v90, v91
	v_cvt_pk_bf16_f32 v90, v80, v81
	v_cvt_pk_bf16_f32 v91, v82, v83
	v_add_u32_e32 v167, 0x30000, v165
	global_store_dwordx4 v167, v[88:91], s[34:35] offset:0
	v_add_u32_e32 v166, 0x140000, v164
	global_load_dwordx4 v[96:99], v166, s[0:1] offset:512
	global_load_dwordx4 v[182:185], v166, s[0:1] offset:528
	v_add_u32_e32 v166, 0x160000, v164
	global_load_dwordx4 v[186:189], v166, s[0:1] offset:0
	global_load_dwordx4 v[80:83], v166, s[0:1] offset:16
	s_waitcnt vmcnt(18)
	v_pk_fma_f32 v[68:69], v[68:69], v[76:77], v[128:129]
	v_pk_fma_f32 v[70:71], v[70:71], v[78:79], v[130:131]
	v_pk_fma_f32 v[64:65], v[64:65], v[72:73], v[190:191]
	v_pk_fma_f32 v[66:67], v[66:67], v[74:75], v[192:193]
	v_cvt_pk_bf16_f32 v68, v68, v69
	v_cvt_pk_bf16_f32 v69, v70, v71
	v_cvt_pk_bf16_f32 v70, v64, v65
	v_cvt_pk_bf16_f32 v71, v66, v67
	v_add_u32_e32 v167, 0x30000, v165
	global_store_dwordx4 v167, v[68:71], s[34:35] offset:256
	v_add_u32_e32 v166, 0x160000, v164
	global_load_dwordx4 v[128:131], v166, s[0:1] offset:512
	global_load_dwordx4 v[190:193], v166, s[0:1] offset:528
	s_waitcnt vmcnt(19)
	v_pk_fma_f32 v[60:61], v[60:61], v[92:93], v[194:195]
	v_pk_fma_f32 v[62:63], v[62:63], v[94:95], v[196:197]
	v_pk_fma_f32 v[56:57], v[56:57], v[84:85], v[120:121]
	v_pk_fma_f32 v[58:59], v[58:59], v[86:87], v[122:123]
	v_cvt_pk_bf16_f32 v60, v60, v61
	v_cvt_pk_bf16_f32 v61, v62, v63
	v_cvt_pk_bf16_f32 v62, v56, v57
	v_cvt_pk_bf16_f32 v63, v58, v59
	v_add_u32_e32 v167, 0x80000, v165
	global_store_dwordx4 v167, v[60:63], s[34:35] offset:0
	s_waitcnt vmcnt(17)
	v_pk_fma_f32 v[52:53], v[52:53], v[76:77], v[198:199]
	v_pk_fma_f32 v[54:55], v[54:55], v[78:79], v[200:201]
	v_pk_fma_f32 v[48:49], v[48:49], v[72:73], v[202:203]
	v_pk_fma_f32 v[50:51], v[50:51], v[74:75], v[204:205]
	v_cvt_pk_bf16_f32 v52, v52, v53
	v_cvt_pk_bf16_f32 v53, v54, v55
	v_cvt_pk_bf16_f32 v54, v48, v49
	v_cvt_pk_bf16_f32 v55, v50, v51
	v_add_u32_e32 v167, 0x80000, v165
	global_store_dwordx4 v167, v[52:55], s[34:35] offset:256
	s_waitcnt vmcnt(15)
	v_pk_fma_f32 v[44:45], v[44:45], v[92:93], v[112:113]
	v_pk_fma_f32 v[46:47], v[46:47], v[94:95], v[114:115]
	v_pk_fma_f32 v[40:41], v[40:41], v[84:85], v[228:229]
	v_pk_fma_f32 v[42:43], v[42:43], v[86:87], v[230:231]
	v_cvt_pk_bf16_f32 v44, v44, v45
	v_cvt_pk_bf16_f32 v45, v46, v47
	v_cvt_pk_bf16_f32 v46, v40, v41
	v_cvt_pk_bf16_f32 v47, v42, v43
	v_add_u32_e32 v167, 0x90000, v165
	global_store_dwordx4 v167, v[44:47], s[34:35] offset:0
	s_waitcnt vmcnt(14)
	v_pk_fma_f32 v[36:37], v[36:37], v[76:77], v[168:169]
	v_pk_fma_f32 v[38:39], v[38:39], v[78:79], v[170:171]
	v_pk_fma_f32 v[32:33], v[32:33], v[72:73], v[104:105]
	v_pk_fma_f32 v[34:35], v[34:35], v[74:75], v[106:107]
	v_cvt_pk_bf16_f32 v36, v36, v37
	v_cvt_pk_bf16_f32 v37, v38, v39
	v_cvt_pk_bf16_f32 v38, v32, v33
	v_cvt_pk_bf16_f32 v39, v34, v35
	v_add_u32_e32 v167, 0x90000, v165
	global_store_dwordx4 v167, v[36:39], s[34:35] offset:256
	s_waitcnt vmcnt(12)
	v_pk_fma_f32 v[28:29], v[28:29], v[92:93], v[178:179]
	v_pk_fma_f32 v[30:31], v[30:31], v[94:95], v[180:181]
	v_pk_fma_f32 v[24:25], v[24:25], v[84:85], v[136:137]
	v_pk_fma_f32 v[26:27], v[26:27], v[86:87], v[138:139]
	v_cvt_pk_bf16_f32 v28, v28, v29
	v_cvt_pk_bf16_f32 v29, v30, v31
	v_cvt_pk_bf16_f32 v30, v24, v25
	v_cvt_pk_bf16_f32 v31, v26, v27
	v_add_u32_e32 v167, 0xa0000, v165
	global_store_dwordx4 v167, v[28:31], s[34:35] offset:0
	s_waitcnt vmcnt(10)
	v_pk_fma_f32 v[20:21], v[20:21], v[76:77], v[96:97]
	v_pk_fma_f32 v[22:23], v[22:23], v[78:79], v[98:99]
	v_pk_fma_f32 v[16:17], v[16:17], v[72:73], v[182:183]
	v_pk_fma_f32 v[18:19], v[18:19], v[74:75], v[184:185]
	v_cvt_pk_bf16_f32 v20, v20, v21
	v_cvt_pk_bf16_f32 v21, v22, v23
	v_cvt_pk_bf16_f32 v22, v16, v17
	v_cvt_pk_bf16_f32 v23, v18, v19
	v_add_u32_e32 v167, 0xa0000, v165
	global_store_dwordx4 v167, v[20:23], s[34:35] offset:256
	s_waitcnt vmcnt(9)
	v_pk_fma_f32 v[12:13], v[12:13], v[92:93], v[186:187]
	v_pk_fma_f32 v[14:15], v[14:15], v[94:95], v[188:189]
	v_pk_fma_f32 v[8:9], v[8:9], v[84:85], v[80:81]
	v_pk_fma_f32 v[10:11], v[10:11], v[86:87], v[82:83]
	v_cvt_pk_bf16_f32 v12, v12, v13
	v_cvt_pk_bf16_f32 v13, v14, v15
	v_cvt_pk_bf16_f32 v14, v8, v9
	v_cvt_pk_bf16_f32 v15, v10, v11
	v_add_u32_e32 v167, 0xb0000, v165
	global_store_dwordx4 v167, v[12:15], s[34:35] offset:0
	s_waitcnt vmcnt(7)
	v_pk_fma_f32 v[4:5], v[4:5], v[76:77], v[128:129]
	v_pk_fma_f32 v[6:7], v[6:7], v[78:79], v[130:131]
	v_pk_fma_f32 v[0:1], v[0:1], v[72:73], v[190:191]
	v_pk_fma_f32 v[2:3], v[2:3], v[74:75], v[192:193]
	v_cvt_pk_bf16_f32 v4, v4, v5
	v_cvt_pk_bf16_f32 v5, v6, v7
	v_cvt_pk_bf16_f32 v6, v0, v1
	v_cvt_pk_bf16_f32 v7, v2, v3
	v_add_u32_e32 v167, 0xb0000, v165
	global_store_dwordx4 v167, v[4:7], s[34:35] offset:256
	s_mov_b64 s[42:43], 0
	s_branch .Lepr1_latch

; #define PG8_STAGE(bufoff, gbase, voff) do { _Pragma("unroll") for (int _i = 0; _i < 2; ++_i) \
;         __builtin_amdgcn_global_load_lds((const unsigned*)((const char*)(gbase) + (voff)[_i]), (LAS unsigned*)(lds + (bufoff) + ldsw + _i * 8192), 16, 0, 0); } while (0)
; #define PG8_LDA(dst, b, h) do { _Pragma("unroll") for (int m = 0; m < 4; ++m) _Pragma("unroll") for (int k = 0; k < 2; ++k) dst[m][k] = *(const LAS bf16x8*)(lds + PG8_SA(b, h) + aoff + m * 2048 + k * 1024); } while (0)
; #define PG8_LDB(dst, b, h) do { _Pragma("unroll") for (int n = 0; n < 2; ++n) _Pragma("unroll") for (int k = 0; k < 2; ++k) dst[n][k] = *(const LAS bf16x8*)(lds + PG8_SB(b, h) + boff + n * 2048 + k * 1024); } while (0)
; #define PG8_MMA(ai, bj, At, Bt) do { __builtin_amdgcn_s_setprio(1); _Pragma("unroll") for (int m = 0; m < 4; ++m) _Pragma("unroll") for (int n = 0; n < 2; ++n) _Pragma("unroll") for (int k = 0; k < 2; ++k) \
;         acc[ai][bj][m][n] = __builtin_amdgcn_mfma_f32_16x16x32_bf16(Bt[n][k], At[m][k], acc[ai][bj][m][n], 0, 0, 0); __builtin_amdgcn_s_setprio(0); } while (0)
; #define PG8_WAIT_V(n) asm volatile("s_waitcnt vmcnt(" #n ")" ::: "memory")
; #define PG8_WAIT_L(n) asm volatile("s_waitcnt lgkmcnt(" #n ")" ::: "memory")
; #define PG8_BAR __builtin_amdgcn_s_barrier()
; #define PG8_SCHED __builtin_amdgcn_sched_barrier(0)
; template <class Epi>
; __device__ __forceinline__ void gemm_phase(LAS unsigned char* lds, const Gemm g, const Epi& E) {
;     ...
;             PG8_LDB(B0, 0, 0); PG8_SCHED; PG8_LDA(At, 0, 0); PG8_STAGE(PG8_SA(1, 1), a1 + hstep, voffA);
;             PG8_WAIT_L(8); PG8_BAR; PG8_WAIT_L(0); PG8_MMA(0, 0, At, B0); PG8_BAR; PG8_SCHED;
;             PG8_LDB(B1, 0, 1); PG8_STAGE(PG8_SB(0, 0), b2, voffB);
;             PG8_BAR; PG8_WAIT_L(0); PG8_MMA(0, 1, At, B1); PG8_BAR;
;             PG8_LDA(At, 0, 1); PG8_STAGE(PG8_SA(0, 0), a2, voffA);
;             PG8_BAR; PG8_WAIT_L(0); PG8_MMA(1, 0, At, B0); PG8_BAR; PG8_SCHED;
;             PG8_STAGE(PG8_SB(0, 1), b2 + hstep, voffB);
;             PG8_WAIT_V(6); PG8_BAR; PG8_MMA(1, 1, At, B1); PG8_BAR;
.LBB0_873:
	s_add_u32 s28, s26, 0x100
	s_addc_u32 s29, s27, 0
	s_add_i32 s34, 0, 0x10000
	v_add_u32_e32 v140, s34, v160
	ds_read_b128 v[128:131], v140
	ds_read_b128 v[132:135], v140 offset:1024
	ds_read_b128 v[136:139], v140 offset:2048
	ds_read_b128 v[140:143], v140 offset:3072
	s_cmpk_eq_i32 s82, 0x54
	s_cselect_b32 s39, s1, s29
	s_cselect_b32 s38, s0, s28
	s_cselect_b32 s37, s43, s79
	s_cselect_b32 s36, s42, s78
	v_lshl_add_u64 v[192:193], s[26:27], 0, v[152:153]
	s_add_i32 m0, s44, 0xc000
	ds_read_b128 v[156:159], v161
	ds_read_b128 v[164:167], v161 offset:1024
	ds_read_b128 v[168:171], v161 offset:2048
	ds_read_b128 v[172:175], v161 offset:3072
	ds_read_b128 v[176:179], v161 offset:4096
	ds_read_b128 v[180:183], v161 offset:5120
	ds_read_b128 v[184:187], v161 offset:6144
	ds_read_b128 v[188:191], v161 offset:7168
	global_load_lds_dwordx4 v[192:193], off
	v_lshl_add_u64 v[192:193], s[26:27], 0, v[154:155]
	s_add_i32 m0, s44, 0xe000
	s_nop 0
	global_load_lds_dwordx4 v[192:193], off
	s_waitcnt lgkmcnt(8)
	s_barrier
	s_waitcnt lgkmcnt(0)
	s_setprio 1
	s_waitcnt lgkmcnt(0)
	v_mfma_f32_16x16x32_bf16 v[124:127], v[128:131], v[156:159], v[124:127]
	v_mfma_f32_16x16x32_bf16 v[120:123], v[136:139], v[156:159], v[120:123]
	v_mfma_f32_16x16x32_bf16 v[108:111], v[128:131], v[168:171], v[108:111]
	v_mfma_f32_16x16x32_bf16 v[104:107], v[136:139], v[168:171], v[104:107]
	v_mfma_f32_16x16x32_bf16 v[92:95], v[128:131], v[176:179], v[92:95]
	v_mfma_f32_16x16x32_bf16 v[88:91], v[136:139], v[176:179], v[88:91]
	v_mfma_f32_16x16x32_bf16 v[76:79], v[128:131], v[184:187], v[76:79]
	v_mfma_f32_16x16x32_bf16 v[72:75], v[136:139], v[184:187], v[72:75]
	v_mfma_f32_16x16x32_bf16 v[124:127], v[132:135], v[164:167], v[124:127]
	v_mfma_f32_16x16x32_bf16 v[120:123], v[140:143], v[164:167], v[120:123]
	v_mfma_f32_16x16x32_bf16 v[108:111], v[132:135], v[172:175], v[108:111]
	v_mfma_f32_16x16x32_bf16 v[104:107], v[140:143], v[172:175], v[104:107]
	v_mfma_f32_16x16x32_bf16 v[92:95], v[132:135], v[180:183], v[92:95]
	v_mfma_f32_16x16x32_bf16 v[88:91], v[140:143], v[180:183], v[88:91]
	v_mfma_f32_16x16x32_bf16 v[76:79], v[132:135], v[188:191], v[76:79]
	v_mfma_f32_16x16x32_bf16 v[72:75], v[140:143], v[188:191], v[72:75]
	s_setprio 0
	s_barrier
	s_add_i32 s35, 0, 0x14000
	s_add_i32 s26, s34, s31
	v_add_u32_e32 v163, s35, v160
	v_lshl_add_u64 v[220:221], s[36:37], 0, v[208:209]
	s_mov_b32 m0, s26
	ds_read_b128 v[192:195], v163
	ds_read_b128 v[196:199], v163 offset:1024
	ds_read_b128 v[200:203], v163 offset:2048
	ds_read_b128 v[204:207], v163 offset:3072
	global_load_lds_dwordx4 v[220:221], off
	v_lshl_add_u64 v[228:229], s[36:37], 0, v[148:149]
	s_add_i32 m0, s26, 0x2000
	s_nop 0
	global_load_lds_dwordx4 v[228:229], off
	s_barrier
	s_waitcnt lgkmcnt(0)
	s_setprio 1
	s_waitcnt lgkmcnt(0)
	v_mfma_f32_16x16x32_bf16 v[116:119], v[192:195], v[156:159], v[116:119]
	v_mfma_f32_16x16x32_bf16 v[112:115], v[200:203], v[156:159], v[112:115]
	v_mfma_f32_16x16x32_bf16 v[100:103], v[192:195], v[168:171], v[100:103]
	v_mfma_f32_16x16x32_bf16 v[96:99], v[200:203], v[168:171], v[96:99]
	v_mfma_f32_16x16x32_bf16 v[84:87], v[192:195], v[176:179], v[84:87]
	v_mfma_f32_16x16x32_bf16 v[80:83], v[200:203], v[176:179], v[80:83]
	v_mfma_f32_16x16x32_bf16 v[68:71], v[192:195], v[184:187], v[68:71]
	v_mfma_f32_16x16x32_bf16 v[64:67], v[200:203], v[184:187], v[64:67]
	v_mfma_f32_16x16x32_bf16 v[116:119], v[196:199], v[164:167], v[116:119]
	v_mfma_f32_16x16x32_bf16 v[112:115], v[204:207], v[164:167], v[112:115]
	v_mfma_f32_16x16x32_bf16 v[100:103], v[196:199], v[172:175], v[100:103]
	v_mfma_f32_16x16x32_bf16 v[96:99], v[204:207], v[172:175], v[96:99]
	v_mfma_f32_16x16x32_bf16 v[84:87], v[196:199], v[180:183], v[84:87]
	v_mfma_f32_16x16x32_bf16 v[80:83], v[204:207], v[180:183], v[80:83]
	v_mfma_f32_16x16x32_bf16 v[68:71], v[196:199], v[188:191], v[68:71]
	v_mfma_f32_16x16x32_bf16 v[64:67], v[204:207], v[188:191], v[64:67]
	s_setprio 0
	s_mov_b32 m0, s44
	v_lshl_add_u64 v[230:231], s[38:39], 0, v[144:145]
	s_barrier
	ds_read_b128 v[156:159], v161 offset:16384
	ds_read_b128 v[164:167], v161 offset:17408
	ds_read_b128 v[168:171], v161 offset:18432
	ds_read_b128 v[172:175], v161 offset:19456
	ds_read_b128 v[176:179], v161 offset:20480
	ds_read_b128 v[180:183], v161 offset:21504
	ds_read_b128 v[184:187], v161 offset:22528
	ds_read_b128 v[188:191], v161 offset:23552
	global_load_lds_dwordx4 v[230:231], off
	v_lshl_add_u64 v[232:233], s[38:39], 0, v[146:147]
	s_mov_b32 m0, s45
	s_nop 0
	global_load_lds_dwordx4 v[232:233], off
	s_barrier
	s_waitcnt lgkmcnt(0)
	s_setprio 1
	s_waitcnt lgkmcnt(0)
	v_mfma_f32_16x16x32_bf16 v[60:63], v[128:131], v[156:159], v[60:63]
	v_mfma_f32_16x16x32_bf16 v[56:59], v[136:139], v[156:159], v[56:59]
	v_mfma_f32_16x16x32_bf16 v[44:47], v[128:131], v[168:171], v[44:47]
	v_mfma_f32_16x16x32_bf16 v[40:43], v[136:139], v[168:171], v[40:43]
	v_mfma_f32_16x16x32_bf16 v[28:31], v[128:131], v[176:179], v[28:31]
	v_mfma_f32_16x16x32_bf16 v[24:27], v[136:139], v[176:179], v[24:27]
	v_mfma_f32_16x16x32_bf16 v[12:15], v[128:131], v[184:187], v[12:15]
	v_mfma_f32_16x16x32_bf16 v[8:11], v[136:139], v[184:187], v[8:11]
	v_mfma_f32_16x16x32_bf16 v[60:63], v[132:135], v[164:167], v[60:63]
	v_mfma_f32_16x16x32_bf16 v[56:59], v[140:143], v[164:167], v[56:59]
	v_mfma_f32_16x16x32_bf16 v[44:47], v[132:135], v[172:175], v[44:47]
	v_mfma_f32_16x16x32_bf16 v[40:43], v[140:143], v[172:175], v[40:43]
	v_mfma_f32_16x16x32_bf16 v[28:31], v[132:135], v[180:183], v[28:31]
	v_mfma_f32_16x16x32_bf16 v[24:27], v[140:143], v[180:183], v[24:27]
	v_mfma_f32_16x16x32_bf16 v[12:15], v[132:135], v[188:191], v[12:15]
	v_mfma_f32_16x16x32_bf16 v[8:11], v[140:143], v[188:191], v[8:11]
	s_setprio 0
	s_barrier
; #define PG8_STAGE(bufoff, gbase, voff) do { _Pragma("unroll") for (int _i = 0; _i < 2; ++_i) \
;         __builtin_amdgcn_global_load_lds((const unsigned*)((const char*)(gbase) + (voff)[_i]), (LAS unsigned*)(lds + (bufoff) + ldsw + _i * 8192), 16, 0, 0); } while (0)
; #define PG8_LDA(dst, b, h) do { _Pragma("unroll") for (int m = 0; m < 4; ++m) _Pragma("unroll") for (int k = 0; k < 2; ++k) dst[m][k] = *(const LAS bf16x8*)(lds + PG8_SA(b, h) + aoff + m * 2048 + k * 1024); } while (0)
; #define PG8_LDB(dst, b, h) do { _Pragma("unroll") for (int n = 0; n < 2; ++n) _Pragma("unroll") for (int k = 0; k < 2; ++k) dst[n][k] = *(const LAS bf16x8*)(lds + PG8_SB(b, h) + boff + n * 2048 + k * 1024); } while (0)
; #define PG8_MMA(ai, bj, At, Bt) do { __builtin_amdgcn_s_setprio(1); _Pragma("unroll") for (int m = 0; m < 4; ++m) _Pragma("unroll") for (int n = 0; n < 2; ++n) _Pragma("unroll") for (int k = 0; k < 2; ++k) \
;         acc[ai][bj][m][n] = __builtin_amdgcn_mfma_f32_16x16x32_bf16(Bt[n][k], At[m][k], acc[ai][bj][m][n], 0, 0, 0); __builtin_amdgcn_s_setprio(0); } while (0)
; #define PG8_WAIT_V(n) asm volatile("s_waitcnt vmcnt(" #n ")" ::: "memory")
; #define PG8_WAIT_L(n) asm volatile("s_waitcnt lgkmcnt(" #n ")" ::: "memory")
; #define PG8_BAR __builtin_amdgcn_s_barrier()
; #define PG8_SCHED __builtin_amdgcn_sched_barrier(0)
; template <class Epi>
; __device__ __forceinline__ void gemm_phase(LAS unsigned char* lds, const Gemm g, const Epi& E) {
;     ...
;             PG8_STAGE(PG8_SB(0, 1), b2 + hstep, voffB);
;             PG8_WAIT_V(6); PG8_BAR; PG8_MMA(1, 1, At, B1); PG8_BAR;
;             PG8_LDB(B0, 1, 0); PG8_SCHED; PG8_LDA(At, 1, 0); PG8_STAGE(PG8_SA(0, 1), a2 + hstep, voffA);
;             PG8_WAIT_L(8); PG8_BAR; PG8_WAIT_L(0); PG8_MMA(0, 0, At, B0); PG8_BAR; PG8_SCHED;
;             PG8_LDB(B1, 1, 1); PG8_STAGE(PG8_SB(1, 0), b3, voffB);
;             PG8_BAR; PG8_WAIT_L(0); PG8_MMA(0, 1, At, B1); PG8_BAR;
;             PG8_LDA(At, 1, 1); PG8_STAGE(PG8_SA(1, 0), a3, voffA);
;             PG8_BAR; PG8_WAIT_L(0); PG8_MMA(1, 0, At, B0); PG8_BAR; PG8_SCHED;
	s_add_u32 s26, s36, 0x160000
	s_addc_u32 s27, s37, 0
	s_add_i32 s34, s35, s31
	v_lshl_add_u64 v[128:129], s[26:27], 0, v[208:209]
	s_mov_b32 m0, s34
	s_nop 0
	global_load_lds_dwordx4 v[128:129], off
	v_lshl_add_u64 v[128:129], s[26:27], 0, v[148:149]
	s_add_i32 m0, s34, 0x2000
	s_nop 0
	global_load_lds_dwordx4 v[128:129], off
	s_waitcnt vmcnt(6)
	s_barrier
	s_setprio 1
	v_mfma_f32_16x16x32_bf16 v[52:55], v[192:195], v[156:159], v[52:55]
	v_mfma_f32_16x16x32_bf16 v[48:51], v[200:203], v[156:159], v[48:51]
	v_mfma_f32_16x16x32_bf16 v[36:39], v[192:195], v[168:171], v[36:39]
	v_mfma_f32_16x16x32_bf16 v[32:35], v[200:203], v[168:171], v[32:35]
	v_mfma_f32_16x16x32_bf16 v[20:23], v[192:195], v[176:179], v[20:23]
	v_mfma_f32_16x16x32_bf16 v[16:19], v[200:203], v[176:179], v[16:19]
	v_mfma_f32_16x16x32_bf16 v[4:7], v[192:195], v[184:187], v[4:7]
	v_mfma_f32_16x16x32_bf16 v[0:3], v[200:203], v[184:187], v[0:3]
	v_mfma_f32_16x16x32_bf16 v[52:55], v[196:199], v[164:167], v[52:55]
	v_mfma_f32_16x16x32_bf16 v[48:51], v[204:207], v[164:167], v[48:51]
	v_mfma_f32_16x16x32_bf16 v[36:39], v[196:199], v[172:175], v[36:39]
	v_mfma_f32_16x16x32_bf16 v[32:35], v[204:207], v[172:175], v[32:35]
	v_mfma_f32_16x16x32_bf16 v[20:23], v[196:199], v[180:183], v[20:23]
	v_mfma_f32_16x16x32_bf16 v[16:19], v[204:207], v[180:183], v[16:19]
	v_mfma_f32_16x16x32_bf16 v[4:7], v[196:199], v[188:191], v[4:7]
	v_mfma_f32_16x16x32_bf16 v[0:3], v[204:207], v[188:191], v[0:3]
	s_setprio 0
	s_add_i32 s34, 0, 0x18000
	v_add_u32_e32 v140, s34, v160
	s_barrier
	ds_read_b128 v[128:131], v140
	ds_read_b128 v[132:135], v140 offset:1024
	ds_read_b128 v[136:139], v140 offset:2048
	ds_read_b128 v[140:143], v140 offset:3072
	s_add_u32 s26, s38, 0x160000
	s_addc_u32 s27, s39, 0
	s_mov_b32 m0, s46
	v_lshl_add_u64 v[192:193], s[26:27], 0, v[144:145]
	ds_read_b128 v[156:159], v161 offset:32768
	ds_read_b128 v[164:167], v161 offset:33792
	ds_read_b128 v[168:171], v161 offset:34816
	ds_read_b128 v[172:175], v161 offset:35840
	ds_read_b128 v[176:179], v161 offset:36864
	ds_read_b128 v[180:183], v161 offset:37888
	ds_read_b128 v[184:187], v161 offset:38912
	ds_read_b128 v[188:191], v161 offset:39936
	global_load_lds_dwordx4 v[192:193], off
	v_lshl_add_u64 v[192:193], s[26:27], 0, v[146:147]
	s_mov_b32 m0, s47
	s_nop 0
	global_load_lds_dwordx4 v[192:193], off
	s_waitcnt lgkmcnt(8)
	s_barrier
	s_waitcnt lgkmcnt(0)
	s_setprio 1
	s_waitcnt lgkmcnt(0)
	v_mfma_f32_16x16x32_bf16 v[124:127], v[128:131], v[156:159], v[124:127]
	v_mfma_f32_16x16x32_bf16 v[120:123], v[136:139], v[156:159], v[120:123]
	v_mfma_f32_16x16x32_bf16 v[108:111], v[128:131], v[168:171], v[108:111]
	v_mfma_f32_16x16x32_bf16 v[104:107], v[136:139], v[168:171], v[104:107]
	v_mfma_f32_16x16x32_bf16 v[92:95], v[128:131], v[176:179], v[92:95]
	v_mfma_f32_16x16x32_bf16 v[88:91], v[136:139], v[176:179], v[88:91]
	v_mfma_f32_16x16x32_bf16 v[76:79], v[128:131], v[184:187], v[76:79]
	v_mfma_f32_16x16x32_bf16 v[72:75], v[136:139], v[184:187], v[72:75]
	v_mfma_f32_16x16x32_bf16 v[124:127], v[132:135], v[164:167], v[124:127]
	v_mfma_f32_16x16x32_bf16 v[120:123], v[140:143], v[164:167], v[120:123]
	v_mfma_f32_16x16x32_bf16 v[108:111], v[132:135], v[172:175], v[108:111]
	v_mfma_f32_16x16x32_bf16 v[104:107], v[140:143], v[172:175], v[104:107]
	v_mfma_f32_16x16x32_bf16 v[92:95], v[132:135], v[180:183], v[92:95]
	v_mfma_f32_16x16x32_bf16 v[88:91], v[140:143], v[180:183], v[88:91]
	v_mfma_f32_16x16x32_bf16 v[76:79], v[132:135], v[188:191], v[76:79]
	v_mfma_f32_16x16x32_bf16 v[72:75], v[140:143], v[188:191], v[72:75]
	s_setprio 0
	s_barrier
	s_add_i32 s35, 0, 0x1c000
	s_add_i32 s26, s34, s31
	v_add_u32_e32 v163, s35, v160
	v_lshl_add_u64 v[220:221], v[220:221], 0, s[20:21]
	s_mov_b32 m0, s26
	ds_read_b128 v[192:195], v163
	ds_read_b128 v[196:199], v163 offset:1024
	ds_read_b128 v[200:203], v163 offset:2048
	ds_read_b128 v[204:207], v163 offset:3072
	global_load_lds_dwordx4 v[220:221], off
	v_lshl_add_u64 v[220:221], v[228:229], 0, s[20:21]
	s_add_i32 m0, s26, 0x2000
	s_nop 0
	global_load_lds_dwordx4 v[220:221], off
	s_barrier
	s_waitcnt lgkmcnt(0)
	s_setprio 1
	s_waitcnt lgkmcnt(0)
	v_mfma_f32_16x16x32_bf16 v[116:119], v[192:195], v[156:159], v[116:119]
	v_mfma_f32_16x16x32_bf16 v[112:115], v[200:203], v[156:159], v[112:115]
	v_mfma_f32_16x16x32_bf16 v[100:103], v[192:195], v[168:171], v[100:103]
	v_mfma_f32_16x16x32_bf16 v[96:99], v[200:203], v[168:171], v[96:99]
	v_mfma_f32_16x16x32_bf16 v[84:87], v[192:195], v[176:179], v[84:87]
	v_mfma_f32_16x16x32_bf16 v[80:83], v[200:203], v[176:179], v[80:83]
	v_mfma_f32_16x16x32_bf16 v[68:71], v[192:195], v[184:187], v[68:71]
	v_mfma_f32_16x16x32_bf16 v[64:67], v[200:203], v[184:187], v[64:67]
	v_mfma_f32_16x16x32_bf16 v[116:119], v[196:199], v[164:167], v[116:119]
	v_mfma_f32_16x16x32_bf16 v[112:115], v[204:207], v[164:167], v[112:115]
	v_mfma_f32_16x16x32_bf16 v[100:103], v[196:199], v[172:175], v[100:103]
	v_mfma_f32_16x16x32_bf16 v[96:99], v[204:207], v[172:175], v[96:99]
	v_mfma_f32_16x16x32_bf16 v[84:87], v[196:199], v[180:183], v[84:87]
	v_mfma_f32_16x16x32_bf16 v[80:83], v[204:207], v[180:183], v[80:83]
	v_mfma_f32_16x16x32_bf16 v[68:71], v[196:199], v[188:191], v[68:71]
	v_mfma_f32_16x16x32_bf16 v[64:67], v[204:207], v[188:191], v[64:67]
	s_setprio 0
	s_mov_b32 m0, s64
	v_lshl_add_u64 v[220:221], v[230:231], 0, s[20:21]
	s_barrier
	ds_read_b128 v[156:159], v161 offset:49152
	ds_read_b128 v[164:167], v161 offset:50176
	ds_read_b128 v[168:171], v161 offset:51200
	ds_read_b128 v[172:175], v161 offset:52224
	ds_read_b128 v[176:179], v161 offset:53248
	ds_read_b128 v[180:183], v161 offset:54272
	ds_read_b128 v[184:187], v161 offset:55296
	ds_read_b128 v[188:191], v161 offset:56320
	global_load_lds_dwordx4 v[220:221], off
	v_lshl_add_u64 v[220:221], v[232:233], 0, s[20:21]
	s_mov_b32 m0, s65
	s_nop 0
	global_load_lds_dwordx4 v[220:221], off
	s_barrier
; __device__ __forceinline__ float bflo(unsigned w) { return __uint_as_float(w << 16); }
; __device__ __forceinline__ float bfhi(unsigned w) { return __uint_as_float(w & 0xffff0000u); }
; __device__ __forceinline__ u32x4 pack8u(f32x4 a, f32x4 b) { u32x4 w = {cvt_pk_bf16(a[0], a[1]), cvt_pk_bf16(a[2], a[3]), cvt_pk_bf16(b[0], b[1]), cvt_pk_bf16(b[2], b[3])}; return w; }
; #define PG8_STAGE(bufoff, gbase, voff) do { _Pragma("unroll") for (int _i = 0; _i < 2; ++_i) \
;         __builtin_amdgcn_global_load_lds((const unsigned*)((const char*)(gbase) + (voff)[_i]), (LAS unsigned*)(lds + (bufoff) + ldsw + _i * 8192), 16, 0, 0); } while (0)
; #define PG8_WAIT_V(n) asm volatile("s_waitcnt vmcnt(" #n ")" ::: "memory")
; #define PG8_WAIT_L(n) asm volatile("s_waitcnt lgkmcnt(" #n ")" ::: "memory")
; template <class Epi>
; __device__ __forceinline__ void gemm_phase(LAS unsigned char* lds, const Gemm g, const Epi& E) {
;     ...
;             PG8_BAR; PG8_WAIT_L(0); PG8_MMA(1, 0, At, B0); PG8_BAR; PG8_SCHED;
;             PG8_STAGE(PG8_SB(1, 1), b3 + hstep, voffB);
;             PG8_WAIT_V(6); PG8_BAR; PG8_MMA(1, 1, At, B1); PG8_BAR;
;         }
;     __device__ __forceinline__ void operator()(const AccT& acc, const Unit& u, int wr, int wc, int fr, int fq) const {
;         const int b = (u.pm * 256) / SEQ;
;         f32x4 gt[2][2];
; #pragma unroll
;         for (int bj = 0; bj < 2; ++bj)
; #pragma unroll
;             for (int n = 0; n < 2; ++n) gt[bj][n] = *(const f32x4*)(GT + (size_t)b * 6 * D + u.pn * 256 + bj * 128 + wc * 32 + fq * 8 + 4 * n);
; #pragma unroll
;         for (int ai = 0; ai < 2; ++ai)
; #pragma unroll
;             for (int m = 0; m < 4; ++m) {
;                 const int row = u.pm * 256 + ai * 128 + wr * 64 + m * 16 + fr;
; #pragma unroll
;                 for (int bj = 0; bj < 2; ++bj) {
;                     const size_t off = (size_t)row * D + u.pn * 256 + bj * 128 + wc * 32 + fq * 8;
;                     f32x4 x0, x1;
;                     if (XINF) { x0 = *(const f32x4*)(XINF + off); x1 = *(const f32x4*)(XINF + off + 4); }
;                     else { const u32x4 w = *(const u32x4*)(XIN16 + off); x0 = (f32x4){bflo(w[0]), bfhi(w[0]), bflo(w[1]), bfhi(w[1])}; x1 = (f32x4){bflo(w[2]), bfhi(w[2]), bflo(w[3]), bfhi(w[3])}; }
;                     *(u32x4*)(XOUT + off) = pack8u(x0 + gt[bj][0] * acc[ai][bj][m][0], x1 + gt[bj][1] * acc[ai][bj][m][1]);
	s_waitcnt lgkmcnt(0)
	s_setprio 1
	s_waitcnt lgkmcnt(0)
	v_mfma_f32_16x16x32_bf16 v[60:63], v[128:131], v[156:159], v[60:63]
	v_mfma_f32_16x16x32_bf16 v[56:59], v[136:139], v[156:159], v[56:59]
	v_mfma_f32_16x16x32_bf16 v[44:47], v[128:131], v[168:171], v[44:47]
	v_mfma_f32_16x16x32_bf16 v[40:43], v[136:139], v[168:171], v[40:43]
	v_mfma_f32_16x16x32_bf16 v[28:31], v[128:131], v[176:179], v[28:31]
	v_mfma_f32_16x16x32_bf16 v[24:27], v[136:139], v[176:179], v[24:27]
	v_mfma_f32_16x16x32_bf16 v[12:15], v[128:131], v[184:187], v[12:15]
	v_mfma_f32_16x16x32_bf16 v[8:11], v[136:139], v[184:187], v[8:11]
	v_mfma_f32_16x16x32_bf16 v[60:63], v[132:135], v[164:167], v[60:63]
	v_mfma_f32_16x16x32_bf16 v[56:59], v[140:143], v[164:167], v[56:59]
	v_mfma_f32_16x16x32_bf16 v[44:47], v[132:135], v[172:175], v[44:47]
	v_mfma_f32_16x16x32_bf16 v[40:43], v[140:143], v[172:175], v[40:43]
	v_mfma_f32_16x16x32_bf16 v[28:31], v[132:135], v[180:183], v[28:31]
	v_mfma_f32_16x16x32_bf16 v[24:27], v[140:143], v[180:183], v[24:27]
	v_mfma_f32_16x16x32_bf16 v[12:15], v[132:135], v[188:191], v[12:15]
	v_mfma_f32_16x16x32_bf16 v[8:11], v[140:143], v[188:191], v[8:11]
	s_setprio 0
	s_barrier
	s_add_u32 s26, s36, 0x160080
	s_addc_u32 s27, s37, 0
	s_add_i32 s34, s35, s31
	v_lshl_add_u64 v[128:129], s[26:27], 0, v[208:209]
	s_mov_b32 m0, s34
	s_nop 0
	global_load_lds_dwordx4 v[128:129], off
	v_lshl_add_u64 v[128:129], s[26:27], 0, v[148:149]
	s_add_i32 m0, s34, 0x2000
	s_nop 0
	global_load_lds_dwordx4 v[128:129], off
	s_waitcnt vmcnt(6)
	s_barrier
	s_setprio 1
	v_mfma_f32_16x16x32_bf16 v[52:55], v[192:195], v[156:159], v[52:55]
	v_mfma_f32_16x16x32_bf16 v[48:51], v[200:203], v[156:159], v[48:51]
	v_mfma_f32_16x16x32_bf16 v[36:39], v[192:195], v[168:171], v[36:39]
	v_mfma_f32_16x16x32_bf16 v[32:35], v[200:203], v[168:171], v[32:35]
	v_mfma_f32_16x16x32_bf16 v[20:23], v[192:195], v[176:179], v[20:23]
	v_mfma_f32_16x16x32_bf16 v[16:19], v[200:203], v[176:179], v[16:19]
	v_mfma_f32_16x16x32_bf16 v[4:7], v[192:195], v[184:187], v[4:7]
	v_mfma_f32_16x16x32_bf16 v[0:3], v[200:203], v[184:187], v[0:3]
	v_mfma_f32_16x16x32_bf16 v[52:55], v[196:199], v[164:167], v[52:55]
	v_mfma_f32_16x16x32_bf16 v[48:51], v[204:207], v[164:167], v[48:51]
	v_mfma_f32_16x16x32_bf16 v[36:39], v[196:199], v[172:175], v[36:39]
	v_mfma_f32_16x16x32_bf16 v[32:35], v[204:207], v[172:175], v[32:35]
	v_mfma_f32_16x16x32_bf16 v[20:23], v[196:199], v[180:183], v[20:23]
	v_mfma_f32_16x16x32_bf16 v[16:19], v[204:207], v[180:183], v[16:19]
	v_mfma_f32_16x16x32_bf16 v[4:7], v[196:199], v[188:191], v[4:7]
	v_mfma_f32_16x16x32_bf16 v[0:3], v[204:207], v[188:191], v[0:3]
	s_setprio 0
	s_add_i32 s82, s82, 2
	s_add_u32 s78, s78, 0x100
	s_addc_u32 s79, s79, 0
	s_cmpk_gt_u32 s82, 0x55
	s_mov_b64 s[26:27], s[28:29]
	s_barrier
	s_cbranch_scc0 .LBB0_873
	s_ashr_i32 s26, s74, 31
	s_lshr_b32 s26, s26, 29
	s_add_i32 s26, s74, s26
	s_ashr_i32 s26, s26, 3
	s_mul_i32 s26, s26, 6
	s_ashr_i32 s27, s26, 31
	s_lshl_b64 s[26:27], s[26:27], 13
	s_add_u32 s28, s48, s26
	s_addc_u32 s29, s49, s27
	s_lshl_b32 s26, s76, 8
	s_ashr_i32 s27, s26, 31
	v_lshl_add_u32 v157, s74, 8, v151
	v_or_b32_e32 v158, s26, v150
	s_lshl_b64 s[26:27], s[26:27], 2
	s_add_u32 s26, s28, s26
	s_addc_u32 s27, s29, s27
	s_add_u32 s26, s26, s69
	s_addc_u32 s27, s27, 0
	global_load_dwordx4 v[140:143], v162, s[26:27]
	global_load_dwordx4 v[136:139], v162, s[26:27] offset:16
	global_load_dwordx4 v[132:135], v162, s[26:27] offset:512
	global_load_dwordx4 v[128:131], v162, s[26:27] offset:528
	v_lshlrev_b32_e32 v156, 1, v158
	v_lshl_add_u32 v156, v157, 12, v156
	v_add_u32_e32 v157, 0x0, v156
	global_load_dwordx4 v[164:167], v157, s[96:97] offset:0
	v_add_u32_e32 v157, 0x0, v156
	global_load_dwordx4 v[168:171], v157, s[96:97] offset:256
	v_add_u32_e32 v157, 0x10000, v156
	global_load_dwordx4 v[172:175], v157, s[96:97] offset:0
	v_add_u32_e32 v157, 0x10000, v156
	global_load_dwordx4 v[184:187], v157, s[96:97] offset:256
	v_add_u32_e32 v157, 0x20000, v156
	global_load_dwordx4 v[188:191], v157, s[96:97] offset:0
	v_add_u32_e32 v157, 0x20000, v156
	global_load_dwordx4 v[192:195], v157, s[96:97] offset:256
	v_add_u32_e32 v157, 0x30000, v156
	global_load_dwordx4 v[196:199], v157, s[96:97] offset:0
	v_add_u32_e32 v157, 0x30000, v156
	global_load_dwordx4 v[200:203], v157, s[96:97] offset:256
	v_add_u32_e32 v157, 0x80000, v156
	global_load_dwordx4 v[204:207], v157, s[96:97] offset:0
	v_add_u32_e32 v157, 0x80000, v156
	global_load_dwordx4 v[228:231], v157, s[96:97] offset:256
	s_waitcnt vmcnt(9)
	v_lshlrev_b32_e32 v176, 16, v164
	v_and_b32_e32 v177, 0xffff0000, v164
	v_lshlrev_b32_e32 v178, 16, v165
	v_and_b32_e32 v179, 0xffff0000, v165
	v_lshlrev_b32_e32 v180, 16, v166
	v_and_b32_e32 v181, 0xffff0000, v166
	v_lshlrev_b32_e32 v182, 16, v167
	v_and_b32_e32 v183, 0xffff0000, v167
	v_pk_fma_f32 v[124:125], v[124:125], v[140:141], v[176:177]
	v_pk_fma_f32 v[126:127], v[126:127], v[142:143], v[178:179]
	v_pk_fma_f32 v[120:121], v[120:121], v[136:137], v[180:181]
	v_pk_fma_f32 v[122:123], v[122:123], v[138:139], v[182:183]
	v_cvt_pk_bf16_f32 v124, v124, v125
	v_cvt_pk_bf16_f32 v125, v126, v127
	v_cvt_pk_bf16_f32 v126, v120, v121
	v_cvt_pk_bf16_f32 v127, v122, v123
	v_add_u32_e32 v158, 0x0, v156
	global_store_dwordx4 v158, v[124:127], s[96:97] offset:0
	v_add_u32_e32 v157, 0x90000, v156
	global_load_dwordx4 v[164:167], v157, s[96:97] offset:0
	v_add_u32_e32 v157, 0x90000, v156
	global_load_dwordx4 v[120:123], v157, s[96:97] offset:256
	s_waitcnt vmcnt(11)
; __device__ __forceinline__ float bflo(unsigned w) { return __uint_as_float(w << 16); }
; __device__ __forceinline__ float bfhi(unsigned w) { return __uint_as_float(w & 0xffff0000u); }
; __device__ __forceinline__ u32x4 pack8u(f32x4 a, f32x4 b) { u32x4 w = {cvt_pk_bf16(a[0], a[1]), cvt_pk_bf16(a[2], a[3]), cvt_pk_bf16(b[0], b[1]), cvt_pk_bf16(b[2], b[3])}; return w; }
;     __device__ __forceinline__ void operator()(const AccT& acc, const Unit& u, int wr, int wc, int fr, int fq) const {
;     ...
;         for (int ai = 0; ai < 2; ++ai)
; #pragma unroll
;             for (int m = 0; m < 4; ++m) {
;                 const int row = u.pm * 256 + ai * 128 + wr * 64 + m * 16 + fr;
; #pragma unroll
;                 for (int bj = 0; bj < 2; ++bj) {
;                     const size_t off = (size_t)row * D + u.pn * 256 + bj * 128 + wc * 32 + fq * 8;
;                     f32x4 x0, x1;
;                     if (XINF) { x0 = *(const f32x4*)(XINF + off); x1 = *(const f32x4*)(XINF + off + 4); }
;                     else { const u32x4 w = *(const u32x4*)(XIN16 + off); x0 = (f32x4){bflo(w[0]), bfhi(w[0]), bflo(w[1]), bfhi(w[1])}; x1 = (f32x4){bflo(w[2]), bfhi(w[2]), bflo(w[3]), bfhi(w[3])}; }
;                     *(u32x4*)(XOUT + off) = pack8u(x0 + gt[bj][0] * acc[ai][bj][m][0], x1 + gt[bj][1] * acc[ai][bj][m][1]);
;                 }
	v_lshlrev_b32_e32 v176, 16, v168
	v_and_b32_e32 v177, 0xffff0000, v168
	v_lshlrev_b32_e32 v178, 16, v169
	v_and_b32_e32 v179, 0xffff0000, v169
	v_lshlrev_b32_e32 v180, 16, v170
	v_and_b32_e32 v181, 0xffff0000, v170
	v_lshlrev_b32_e32 v182, 16, v171
	v_and_b32_e32 v183, 0xffff0000, v171
	v_pk_fma_f32 v[116:117], v[116:117], v[132:133], v[176:177]
	v_pk_fma_f32 v[118:119], v[118:119], v[134:135], v[178:179]
	v_pk_fma_f32 v[112:113], v[112:113], v[128:129], v[180:181]
	v_pk_fma_f32 v[114:115], v[114:115], v[130:131], v[182:183]
	v_cvt_pk_bf16_f32 v116, v116, v117
	v_cvt_pk_bf16_f32 v117, v118, v119
	v_cvt_pk_bf16_f32 v118, v112, v113
	v_cvt_pk_bf16_f32 v119, v114, v115
	v_add_u32_e32 v158, 0x0, v156
	global_store_dwordx4 v158, v[116:119], s[96:97] offset:256
	v_add_u32_e32 v157, 0xa0000, v156
	global_load_dwordx4 v[168:171], v157, s[96:97] offset:0
	v_add_u32_e32 v157, 0xa0000, v156
	global_load_dwordx4 v[112:115], v157, s[96:97] offset:256
	s_waitcnt vmcnt(13)
	v_lshlrev_b32_e32 v176, 16, v172
	v_and_b32_e32 v177, 0xffff0000, v172
	v_lshlrev_b32_e32 v178, 16, v173
	v_and_b32_e32 v179, 0xffff0000, v173
	v_lshlrev_b32_e32 v180, 16, v174
	v_and_b32_e32 v181, 0xffff0000, v174
	v_lshlrev_b32_e32 v182, 16, v175
	v_and_b32_e32 v183, 0xffff0000, v175
	v_pk_fma_f32 v[108:109], v[108:109], v[140:141], v[176:177]
	v_pk_fma_f32 v[110:111], v[110:111], v[142:143], v[178:179]
	v_pk_fma_f32 v[104:105], v[104:105], v[136:137], v[180:181]
	v_pk_fma_f32 v[106:107], v[106:107], v[138:139], v[182:183]
	v_cvt_pk_bf16_f32 v108, v108, v109
	v_cvt_pk_bf16_f32 v109, v110, v111
	v_cvt_pk_bf16_f32 v110, v104, v105
	v_cvt_pk_bf16_f32 v111, v106, v107
	v_add_u32_e32 v158, 0x10000, v156
	global_store_dwordx4 v158, v[108:111], s[96:97] offset:0
	v_add_u32_e32 v157, 0xb0000, v156
	global_load_dwordx4 v[172:175], v157, s[96:97] offset:0
	v_add_u32_e32 v157, 0xb0000, v156
	global_load_dwordx4 v[104:107], v157, s[96:97] offset:256
	s_waitcnt vmcnt(15)
	v_lshlrev_b32_e32 v176, 16, v184
	v_and_b32_e32 v177, 0xffff0000, v184
	v_lshlrev_b32_e32 v178, 16, v185
	v_and_b32_e32 v179, 0xffff0000, v185
	v_lshlrev_b32_e32 v180, 16, v186
	v_and_b32_e32 v181, 0xffff0000, v186
	v_lshlrev_b32_e32 v182, 16, v187
	v_and_b32_e32 v183, 0xffff0000, v187
	v_pk_fma_f32 v[100:101], v[100:101], v[132:133], v[176:177]
	v_pk_fma_f32 v[102:103], v[102:103], v[134:135], v[178:179]
	v_pk_fma_f32 v[96:97], v[96:97], v[128:129], v[180:181]
	v_pk_fma_f32 v[98:99], v[98:99], v[130:131], v[182:183]
	v_cvt_pk_bf16_f32 v100, v100, v101
	v_cvt_pk_bf16_f32 v101, v102, v103
	v_cvt_pk_bf16_f32 v102, v96, v97
	v_cvt_pk_bf16_f32 v103, v98, v99
	v_add_u32_e32 v158, 0x10000, v156
	global_store_dwordx4 v158, v[100:103], s[96:97] offset:256
	s_waitcnt vmcnt(15)
	v_lshlrev_b32_e32 v176, 16, v188
	v_and_b32_e32 v177, 0xffff0000, v188
	v_lshlrev_b32_e32 v178, 16, v189
	v_and_b32_e32 v179, 0xffff0000, v189
	v_lshlrev_b32_e32 v180, 16, v190
	v_and_b32_e32 v181, 0xffff0000, v190
	v_lshlrev_b32_e32 v182, 16, v191
	v_and_b32_e32 v183, 0xffff0000, v191
	v_pk_fma_f32 v[92:93], v[92:93], v[140:141], v[176:177]
	v_pk_fma_f32 v[94:95], v[94:95], v[142:143], v[178:179]
	v_pk_fma_f32 v[88:89], v[88:89], v[136:137], v[180:181]
	v_pk_fma_f32 v[90:91], v[90:91], v[138:139], v[182:183]
	v_cvt_pk_bf16_f32 v92, v92, v93
	v_cvt_pk_bf16_f32 v93, v94, v95
	v_cvt_pk_bf16_f32 v94, v88, v89
	v_cvt_pk_bf16_f32 v95, v90, v91
	v_add_u32_e32 v158, 0x20000, v156
	global_store_dwordx4 v158, v[92:95], s[96:97] offset:0
	s_waitcnt vmcnt(15)
	v_lshlrev_b32_e32 v176, 16, v192
	v_and_b32_e32 v177, 0xffff0000, v192
	v_lshlrev_b32_e32 v178, 16, v193
	v_and_b32_e32 v179, 0xffff0000, v193
	v_lshlrev_b32_e32 v180, 16, v194
	v_and_b32_e32 v181, 0xffff0000, v194
	v_lshlrev_b32_e32 v182, 16, v195
	v_and_b32_e32 v183, 0xffff0000, v195
	v_pk_fma_f32 v[84:85], v[84:85], v[132:133], v[176:177]
	v_pk_fma_f32 v[86:87], v[86:87], v[134:135], v[178:179]
	v_pk_fma_f32 v[80:81], v[80:81], v[128:129], v[180:181]
	v_pk_fma_f32 v[82:83], v[82:83], v[130:131], v[182:183]
	v_cvt_pk_bf16_f32 v84, v84, v85
	v_cvt_pk_bf16_f32 v85, v86, v87
	v_cvt_pk_bf16_f32 v86, v80, v81
	v_cvt_pk_bf16_f32 v87, v82, v83
	v_add_u32_e32 v158, 0x20000, v156
	global_store_dwordx4 v158, v[84:87], s[96:97] offset:256
	s_waitcnt vmcnt(15)
	v_lshlrev_b32_e32 v176, 16, v196
	v_and_b32_e32 v177, 0xffff0000, v196
	v_lshlrev_b32_e32 v178, 16, v197
	v_and_b32_e32 v179, 0xffff0000, v197
	v_lshlrev_b32_e32 v180, 16, v198
	v_and_b32_e32 v181, 0xffff0000, v198
	v_lshlrev_b32_e32 v182, 16, v199
	v_and_b32_e32 v183, 0xffff0000, v199
	v_pk_fma_f32 v[76:77], v[76:77], v[140:141], v[176:177]
	v_pk_fma_f32 v[78:79], v[78:79], v[142:143], v[178:179]
	v_pk_fma_f32 v[72:73], v[72:73], v[136:137], v[180:181]
	v_pk_fma_f32 v[74:75], v[74:75], v[138:139], v[182:183]
	v_cvt_pk_bf16_f32 v76, v76, v77
	v_cvt_pk_bf16_f32 v77, v78, v79
	v_cvt_pk_bf16_f32 v78, v72, v73
	v_cvt_pk_bf16_f32 v79, v74, v75
	v_add_u32_e32 v158, 0x30000, v156
	global_store_dwordx4 v158, v[76:79], s[96:97] offset:0
	s_waitcnt vmcnt(15)
	v_lshlrev_b32_e32 v176, 16, v200
	v_and_b32_e32 v177, 0xffff0000, v200
	v_lshlrev_b32_e32 v178, 16, v201
	v_and_b32_e32 v179, 0xffff0000, v201
	v_lshlrev_b32_e32 v180, 16, v202
	v_and_b32_e32 v181, 0xffff0000, v202
	v_lshlrev_b32_e32 v182, 16, v203
	v_and_b32_e32 v183, 0xffff0000, v203
	v_pk_fma_f32 v[68:69], v[68:69], v[132:133], v[176:177]
	v_pk_fma_f32 v[70:71], v[70:71], v[134:135], v[178:179]
	v_pk_fma_f32 v[64:65], v[64:65], v[128:129], v[180:181]
	v_pk_fma_f32 v[66:67], v[66:67], v[130:131], v[182:183]
	v_cvt_pk_bf16_f32 v68, v68, v69
	v_cvt_pk_bf16_f32 v69, v70, v71
	v_cvt_pk_bf16_f32 v70, v64, v65
	v_cvt_pk_bf16_f32 v71, v66, v67
	v_add_u32_e32 v158, 0x30000, v156
	global_store_dwordx4 v158, v[68:71], s[96:97] offset:256
	s_waitcnt vmcnt(15)
; __device__ __forceinline__ float bflo(unsigned w) { return __uint_as_float(w << 16); }
; __device__ __forceinline__ float bfhi(unsigned w) { return __uint_as_float(w & 0xffff0000u); }
; __device__ __forceinline__ u32x4 pack8u(f32x4 a, f32x4 b) { u32x4 w = {cvt_pk_bf16(a[0], a[1]), cvt_pk_bf16(a[2], a[3]), cvt_pk_bf16(b[0], b[1]), cvt_pk_bf16(b[2], b[3])}; return w; }
;     __device__ __forceinline__ void operator()(const AccT& acc, const Unit& u, int wr, int wc, int fr, int fq) const {
;     ...
;         for (int ai = 0; ai < 2; ++ai)
; #pragma unroll
;             for (int m = 0; m < 4; ++m) {
;                 const int row = u.pm * 256 + ai * 128 + wr * 64 + m * 16 + fr;
; #pragma unroll
;                 for (int bj = 0; bj < 2; ++bj) {
;                     const size_t off = (size_t)row * D + u.pn * 256 + bj * 128 + wc * 32 + fq * 8;
;                     f32x4 x0, x1;
;                     if (XINF) { x0 = *(const f32x4*)(XINF + off); x1 = *(const f32x4*)(XINF + off + 4); }
;                     else { const u32x4 w = *(const u32x4*)(XIN16 + off); x0 = (f32x4){bflo(w[0]), bfhi(w[0]), bflo(w[1]), bfhi(w[1])}; x1 = (f32x4){bflo(w[2]), bfhi(w[2]), bflo(w[3]), bfhi(w[3])}; }
;                     *(u32x4*)(XOUT + off) = pack8u(x0 + gt[bj][0] * acc[ai][bj][m][0], x1 + gt[bj][1] * acc[ai][bj][m][1]);
;                 }
	v_lshlrev_b32_e32 v176, 16, v204
	v_and_b32_e32 v177, 0xffff0000, v204
	v_lshlrev_b32_e32 v178, 16, v205
	v_and_b32_e32 v179, 0xffff0000, v205
	v_lshlrev_b32_e32 v180, 16, v206
	v_and_b32_e32 v181, 0xffff0000, v206
	v_lshlrev_b32_e32 v182, 16, v207
	v_and_b32_e32 v183, 0xffff0000, v207
	v_pk_fma_f32 v[60:61], v[60:61], v[140:141], v[176:177]
	v_pk_fma_f32 v[62:63], v[62:63], v[142:143], v[178:179]
	v_pk_fma_f32 v[56:57], v[56:57], v[136:137], v[180:181]
	v_pk_fma_f32 v[58:59], v[58:59], v[138:139], v[182:183]
	v_cvt_pk_bf16_f32 v60, v60, v61
	v_cvt_pk_bf16_f32 v61, v62, v63
	v_cvt_pk_bf16_f32 v62, v56, v57
	v_cvt_pk_bf16_f32 v63, v58, v59
	v_add_u32_e32 v158, 0x80000, v156
	global_store_dwordx4 v158, v[60:63], s[96:97] offset:0
	s_waitcnt vmcnt(15)
	v_lshlrev_b32_e32 v176, 16, v228
	v_and_b32_e32 v177, 0xffff0000, v228
	v_lshlrev_b32_e32 v178, 16, v229
	v_and_b32_e32 v179, 0xffff0000, v229
	v_lshlrev_b32_e32 v180, 16, v230
	v_and_b32_e32 v181, 0xffff0000, v230
	v_lshlrev_b32_e32 v182, 16, v231
	v_and_b32_e32 v183, 0xffff0000, v231
	v_pk_fma_f32 v[52:53], v[52:53], v[132:133], v[176:177]
	v_pk_fma_f32 v[54:55], v[54:55], v[134:135], v[178:179]
	v_pk_fma_f32 v[48:49], v[48:49], v[128:129], v[180:181]
	v_pk_fma_f32 v[50:51], v[50:51], v[130:131], v[182:183]
	v_cvt_pk_bf16_f32 v52, v52, v53
	v_cvt_pk_bf16_f32 v53, v54, v55
	v_cvt_pk_bf16_f32 v54, v48, v49
	v_cvt_pk_bf16_f32 v55, v50, v51
	v_add_u32_e32 v158, 0x80000, v156
	global_store_dwordx4 v158, v[52:55], s[96:97] offset:256
	s_waitcnt vmcnt(14)
	v_lshlrev_b32_e32 v176, 16, v164
	v_and_b32_e32 v177, 0xffff0000, v164
	v_lshlrev_b32_e32 v178, 16, v165
	v_and_b32_e32 v179, 0xffff0000, v165
	v_lshlrev_b32_e32 v180, 16, v166
	v_and_b32_e32 v181, 0xffff0000, v166
	v_lshlrev_b32_e32 v182, 16, v167
	v_and_b32_e32 v183, 0xffff0000, v167
	v_pk_fma_f32 v[44:45], v[44:45], v[140:141], v[176:177]
	v_pk_fma_f32 v[46:47], v[46:47], v[142:143], v[178:179]
	v_pk_fma_f32 v[40:41], v[40:41], v[136:137], v[180:181]
	v_pk_fma_f32 v[42:43], v[42:43], v[138:139], v[182:183]
	v_cvt_pk_bf16_f32 v44, v44, v45
	v_cvt_pk_bf16_f32 v45, v46, v47
	v_cvt_pk_bf16_f32 v46, v40, v41
	v_cvt_pk_bf16_f32 v47, v42, v43
	v_add_u32_e32 v158, 0x90000, v156
	global_store_dwordx4 v158, v[44:47], s[96:97] offset:0
	s_waitcnt vmcnt(14)
	v_lshlrev_b32_e32 v176, 16, v120
	v_and_b32_e32 v177, 0xffff0000, v120
	v_lshlrev_b32_e32 v178, 16, v121
	v_and_b32_e32 v179, 0xffff0000, v121
	v_lshlrev_b32_e32 v180, 16, v122
	v_and_b32_e32 v181, 0xffff0000, v122
	v_lshlrev_b32_e32 v182, 16, v123
	v_and_b32_e32 v183, 0xffff0000, v123
	v_pk_fma_f32 v[36:37], v[36:37], v[132:133], v[176:177]
	v_pk_fma_f32 v[38:39], v[38:39], v[134:135], v[178:179]
	v_pk_fma_f32 v[32:33], v[32:33], v[128:129], v[180:181]
	v_pk_fma_f32 v[34:35], v[34:35], v[130:131], v[182:183]
	v_cvt_pk_bf16_f32 v36, v36, v37
	v_cvt_pk_bf16_f32 v37, v38, v39
	v_cvt_pk_bf16_f32 v38, v32, v33
	v_cvt_pk_bf16_f32 v39, v34, v35
	v_add_u32_e32 v158, 0x90000, v156
	global_store_dwordx4 v158, v[36:39], s[96:97] offset:256
	s_waitcnt vmcnt(13)
	v_lshlrev_b32_e32 v176, 16, v168
	v_and_b32_e32 v177, 0xffff0000, v168
	v_lshlrev_b32_e32 v178, 16, v169
	v_and_b32_e32 v179, 0xffff0000, v169
	v_lshlrev_b32_e32 v180, 16, v170
	v_and_b32_e32 v181, 0xffff0000, v170
	v_lshlrev_b32_e32 v182, 16, v171
	v_and_b32_e32 v183, 0xffff0000, v171
	v_pk_fma_f32 v[28:29], v[28:29], v[140:141], v[176:177]
	v_pk_fma_f32 v[30:31], v[30:31], v[142:143], v[178:179]
	v_pk_fma_f32 v[24:25], v[24:25], v[136:137], v[180:181]
	v_pk_fma_f32 v[26:27], v[26:27], v[138:139], v[182:183]
	v_cvt_pk_bf16_f32 v28, v28, v29
	v_cvt_pk_bf16_f32 v29, v30, v31
	v_cvt_pk_bf16_f32 v30, v24, v25
	v_cvt_pk_bf16_f32 v31, v26, v27
	v_add_u32_e32 v158, 0xa0000, v156
	global_store_dwordx4 v158, v[28:31], s[96:97] offset:0
	s_waitcnt vmcnt(13)
	v_lshlrev_b32_e32 v176, 16, v112
	v_and_b32_e32 v177, 0xffff0000, v112
	v_lshlrev_b32_e32 v178, 16, v113
	v_and_b32_e32 v179, 0xffff0000, v113
	v_lshlrev_b32_e32 v180, 16, v114
	v_and_b32_e32 v181, 0xffff0000, v114
	v_lshlrev_b32_e32 v182, 16, v115
	v_and_b32_e32 v183, 0xffff0000, v115
	v_pk_fma_f32 v[20:21], v[20:21], v[132:133], v[176:177]
	v_pk_fma_f32 v[22:23], v[22:23], v[134:135], v[178:179]
	v_pk_fma_f32 v[16:17], v[16:17], v[128:129], v[180:181]
	v_pk_fma_f32 v[18:19], v[18:19], v[130:131], v[182:183]
	v_cvt_pk_bf16_f32 v20, v20, v21
	v_cvt_pk_bf16_f32 v21, v22, v23
	v_cvt_pk_bf16_f32 v22, v16, v17
	v_cvt_pk_bf16_f32 v23, v18, v19
	v_add_u32_e32 v158, 0xa0000, v156
	global_store_dwordx4 v158, v[20:23], s[96:97] offset:256
	s_waitcnt vmcnt(12)
	v_lshlrev_b32_e32 v176, 16, v172
	v_and_b32_e32 v177, 0xffff0000, v172
	v_lshlrev_b32_e32 v178, 16, v173
	v_and_b32_e32 v179, 0xffff0000, v173
	v_lshlrev_b32_e32 v180, 16, v174
	v_and_b32_e32 v181, 0xffff0000, v174
	v_lshlrev_b32_e32 v182, 16, v175
	v_and_b32_e32 v183, 0xffff0000, v175
	v_pk_fma_f32 v[12:13], v[12:13], v[140:141], v[176:177]
	v_pk_fma_f32 v[14:15], v[14:15], v[142:143], v[178:179]
	v_pk_fma_f32 v[8:9], v[8:9], v[136:137], v[180:181]
	v_pk_fma_f32 v[10:11], v[10:11], v[138:139], v[182:183]
	v_cvt_pk_bf16_f32 v12, v12, v13
	v_cvt_pk_bf16_f32 v13, v14, v15
	v_cvt_pk_bf16_f32 v14, v8, v9
	v_cvt_pk_bf16_f32 v15, v10, v11
	v_add_u32_e32 v158, 0xb0000, v156
	global_store_dwordx4 v158, v[12:15], s[96:97] offset:0
	s_waitcnt vmcnt(12)
	v_lshlrev_b32_e32 v176, 16, v104
	v_and_b32_e32 v177, 0xffff0000, v104
	v_lshlrev_b32_e32 v178, 16, v105
	v_and_b32_e32 v179, 0xffff0000, v105
	v_lshlrev_b32_e32 v180, 16, v106
	v_and_b32_e32 v181, 0xffff0000, v106
	v_lshlrev_b32_e32 v182, 16, v107
	v_and_b32_e32 v183, 0xffff0000, v107
	v_pk_fma_f32 v[4:5], v[4:5], v[132:133], v[176:177]
	v_pk_fma_f32 v[6:7], v[6:7], v[134:135], v[178:179]
	v_pk_fma_f32 v[0:1], v[0:1], v[128:129], v[180:181]
	v_pk_fma_f32 v[2:3], v[2:3], v[130:131], v[182:183]
	v_cvt_pk_bf16_f32 v4, v4, v5
	v_cvt_pk_bf16_f32 v5, v6, v7
	v_cvt_pk_bf16_f32 v6, v0, v1
	v_cvt_pk_bf16_f32 v7, v2, v3
	v_add_u32_e32 v158, 0xb0000, v156
	global_store_dwordx4 v158, v[4:7], s[96:97] offset:256
	s_mov_b64 s[28:29], s[42:43]
	s_mov_b64 s[26:27], s[0:1]
	s_mov_b32 s74, s71
	s_mov_b32 s76, s70
	s_and_b64 vcc, exec, s[40:41]
	v_readlane_b32 s82, v255, 24
	v_readlane_b32 s83, v255, 25
	s_cbranch_vccz .LBB0_862
	s_waitcnt vmcnt(0)
	s_cmpk_gt_u32 s3, 0xff
	s_cbranch_scc1 .LBB0_877
	s_barrier
